# baseline (speedup 1.0000x reference)
; __device__ __forceinline__ void attn_body256(const bf16_t* __restrict__ Qb, const bf16_t* __restrict__ Kh, const bf16_t* __restrict__ Vh,
;                                              bf16_t* Ob, int seq, unsigned char* lds, float lam, int MODE, bf16_t* Ab, const float* wsub) {
;     ...
;   unsigned koff[2], voff[4];
; #pragma unroll
;   for (int i = 0; i < 2; ++i) { const int o = i * 8192 + tid * 16; const int row = o >> 8; const int colB = (o & 255) ^ ((row & 7) << 4);
;     koff[i] = (unsigned)(row * LDK + (colB >> 1));
;     const int sub = o >> 9, kk = (sub >> 2) * 8 + ((o & 511) >> 6), c = (sub & 3) * 32 + (((o & 511) >> 1) & 31);
;     const int k = (kk & ~0xC) | ((kk & 4) << 1) | ((kk & 8) >> 1);
;     voff[i] = (unsigned)(k * LDK + c); voff[2 + i] = (unsigned)(k * LDK + 128 + c); }
;     ...
;   const int NT = seq / KVBLK;
;   A2_DMA(0, 0); A2_DMA(1, 1);
;   float m_reg = -1e30f, l_reg = 0; f32x16 o[8] = {}; bf16x8 qr[8];
;   const bf16_t* Qw = Qb + (long)(wid * QBLK + r32) * LDQ + hi * 8;
; #pragma unroll
;   for (int d0 = 0; d0 < 8; ++d0) qr[d0] = *reinterpret_cast<const bf16x8*>(Qw + d0 * 16);
.LBB0_669:
	s_and_b32 s2, s18, 1
	s_lshl_b64 s[10:11], s[62:63], 11
	s_lshl_b64 s[6:7], s[62:63], 12
	s_add_u32 s9, s96, s6
	s_addc_u32 s12, s97, s7
	s_lshl_b32 s16, s8, 8
	s_lshl_b32 s6, s2, 7
	s_or_b32 s6, s16, s6
	s_ashr_i32 s7, s6, 31
	s_lshl_b64 s[14:15], s[6:7], 1
	s_add_u32 s6, s9, s14
	s_addc_u32 s7, s12, s15
	s_lshl_b64 s[8:9], s[0:1], 1
	s_add_u32 s0, s60, s8
	s_addc_u32 s1, s53, s9
	s_add_u32 s12, s0, s14
	s_addc_u32 s13, s1, s15
	v_mov_b32 v16, v231
	v_lshrrev_b32_e32 v245, 7, v231
	v_lshlrev_b32_e32 v245, 3, v245
	v_bfe_u32 v244, v231, 1, 3
	v_add_u32_e32 v245, v245, v244
	v_lshlrev_b32_e32 v245, 11, v245
	v_bfe_u32 v244, v231, 4, 3
	v_lshl_add_u32 v245, v244, 4, v245
	v_and_b32_e32 v244, 1, v231
	v_lshl_add_u32 v245, v244, 3, v245
	s_add_u32 s20, s61, s8
	v_lshlrev_b32_e32 v17, 4, v16
	v_add_u32_e32 v6, 0x2000, v17
	s_addc_u32 s21, s68, s9
	s_ashr_i32 s17, s16, 31
	v_ashrrev_i32_e32 v8, 8, v6
	s_lshl_b64 s[0:1], s[16:17], 1
	v_and_b32_e32 v3, 0xf0, v17
	v_lshlrev_b32_e32 v6, 4, v8
	s_movk_i32 s26, 0x70
	s_add_u32 s16, s20, s0
	v_lshrrev_b32_e32 v0, 1, v16
	v_ashrrev_i32_e32 v2, 4, v16
	v_bitop3_b32 v3, v6, v3, s26 bitop3:0x6c
	s_addc_u32 s17, s21, s1
	v_readfirstlane_b32 s20, v16
	v_and_b32_e32 v22, 8, v0
	v_and_b32_e32 v0, 0x70, v16
	s_movk_i32 s21, 0xf0
	v_lshrrev_b32_e32 v4, 1, v2
	v_lshrrev_b32_e32 v3, 1, v3
	s_ashr_i32 s23, s20, 6
	v_bfe_u32 v18, v16, 2, 2
	v_lshlrev_b32_e32 v20, 3, v16
	v_bitop3_b32 v0, v17, v0, s21 bitop3:0x6c
	v_and_b32_e32 v4, 4, v4
	v_lshl_or_b32 v6, v8, 11, v3
	v_and_b32_e32 v3, 0x1ffff0, v8
	v_lshrrev_b32_e32 v8, 1, v8
	v_and_b32_e32 v19, 0x60, v16
	v_and_b32_e32 v21, 24, v20
	v_or_b32_e32 v7, v22, v18
	v_lshrrev_b32_e32 v0, 1, v0
	v_and_or_b32 v23, v2, -16, v4
	v_and_b32_e32 v8, 4, v8
	s_lshl_b32 s21, s23, 10
	v_or_b32_e32 v5, v21, v19
	v_lshl_or_b32 v0, v2, 11, v0
	v_or_b32_e32 v2, v7, v23
	v_or3_b32 v3, v3, v8, v7
	s_add_i32 s21, s21, 0
	v_lshl_or_b32 v2, v2, 11, v5
	v_mov_b32_e32 v2, v245
	v_lshlrev_b32_e32 v24, 11, v3
	s_add_i32 s22, s21, 0x10000
	v_lshlrev_b64 v[12:13], 1, v[0:1]
	v_mov_b32_e32 v3, v1
	v_or_b32_e32 v4, 0x80, v2
	v_lshl_add_u64 v[14:15], s[12:13], 0, v[12:13]
	s_mov_b32 m0, s22
	v_lshlrev_b64 v[2:3], 1, v[2:3]
	s_add_i32 s24, s21, 0x4000
	global_load_lds_dwordx4 v[14:15], off
	v_lshl_add_u64 v[14:15], s[16:17], 0, v[2:3]
	s_mov_b32 m0, s21
	s_mov_b64 s[30:31], 0x100
	v_mov_b32_e32 v7, v1
	s_and_b32 s20, s20, 0x3fffffc0
	v_or_b32_e32 v8, v24, v5
	v_add_u32_e32 v8, 0x10000, v245
	global_load_lds_dwordx4 v[14:15], off
	v_lshl_add_u64 v[14:15], v[14:15], 0, s[30:31]
	s_mov_b32 m0, s24
	v_lshlrev_b64 v[6:7], 1, v[6:7]
	v_mov_b32_e32 v9, v1
	s_lshl_b32 s20, s20, 2
	v_or_b32_e32 v10, 0x80, v8
	global_load_lds_dwordx4 v[14:15], off
	v_lshl_add_u64 v[14:15], s[12:13], 0, v[6:7]
	s_add_i32 m0, s21, 0x12000
	v_lshlrev_b64 v[8:9], 1, v[8:9]
	s_add_i32 s20, s20, 0
	global_load_lds_dwordx4 v[14:15], off
	v_lshl_add_u64 v[14:15], s[16:17], 0, v[8:9]
	s_add_i32 m0, s21, 0x2000
	s_add_i32 s20, s20, 0x18000
	global_load_lds_dwordx4 v[14:15], off
	s_add_i32 m0, s21, 0x6000
	s_add_u32 s12, s12, 0x40000
	s_addc_u32 s13, s13, 0
	v_lshl_add_u64 v[14:15], v[14:15], 0, s[30:31]
	s_add_u32 s16, s16, 0x40000
	global_load_lds_dwordx4 v[14:15], off
	s_addc_u32 s17, s17, 0
	s_add_i32 m0, s21, 0x14000
	s_add_i32 s24, s21, 0x8000
	v_lshl_add_u64 v[14:15], s[12:13], 0, v[12:13]
	v_mov_b32_e32 v5, v1
	s_add_i32 s25, s21, 0xc000
	global_load_lds_dwordx4 v[14:15], off
	v_lshl_add_u64 v[2:3], s[16:17], 0, v[2:3]
	s_mov_b32 m0, s24
	v_mov_b32_e32 v11, v1
	global_load_lds_dwordx4 v[2:3], off
	v_lshl_add_u64 v[2:3], v[4:5], 1, s[16:17]
	s_mov_b32 m0, s25
	v_and_b32_e32 v228, 31, v16
	global_load_lds_dwordx4 v[2:3], off
	v_lshl_add_u64 v[2:3], s[12:13], 0, v[6:7]
	s_add_i32 m0, s21, 0x16000
	s_lshl_b32 s12, s23, 5
	global_load_lds_dwordx4 v[2:3], off
	v_lshl_add_u64 v[2:3], s[16:17], 0, v[8:9]
	s_add_i32 m0, s21, 0xa000
	v_bfe_u32 v229, v16, 5, 1
	global_load_lds_dwordx4 v[2:3], off
	v_lshl_add_u64 v[2:3], v[10:11], 1, s[16:17]
	s_add_i32 m0, s21, 0xe000
	v_lshlrev_b32_e32 v0, 4, v229
	global_load_lds_dwordx4 v[2:3], off
	v_and_b32_e32 v2, 15, v231
	v_or_b32_e32 v2, s12, v2
	v_mov_b32_e32 v3, 0
	v_lshlrev_b64 v[2:3], 12, v[2:3]
	v_lshl_add_u64 v[2:3], s[6:7], 0, v[2:3]
	v_bfe_u32 v194, v231, 4, 2
	v_lshlrev_b32_e32 v194, 4, v194
	v_mov_b32_e32 v195, 0
	v_lshl_add_u64 v[2:3], v[2:3], 0, v[194:195]
	global_load_dwordx4 v[162:165], v[2:3], off
	global_load_dwordx4 v[166:169], v[2:3], off offset:64
	global_load_dwordx4 v[170:173], v[2:3], off offset:128
	global_load_dwordx4 v[174:177], v[2:3], off offset:192
	v_mov_b32_e32 v194, 0x10000
	v_lshl_add_u64 v[2:3], v[2:3], 0, v[194:195]
	global_load_dwordx4 v[178:181], v[2:3], off
	global_load_dwordx4 v[182:185], v[2:3], off offset:64
	global_load_dwordx4 v[186:189], v[2:3], off offset:128
	global_load_dwordx4 v[190:193], v[2:3], off offset:192
	v_and_b32_e32 v8, 0x70, v17
	s_movk_i32 s6, 0x60
	v_bitop3_b32 v236, v0, v8, s6 bitop3:0x36
	s_movk_i32 s6, 0x80
	v_bitop3_b32 v237, v0, v8, s6 bitop3:0x36
	s_movk_i32 s6, 0xa0
	v_bitop3_b32 v240, v0, v8, s6 bitop3:0x36
	s_movk_i32 s6, 0xc0
	s_cmp_lg_u32 0, -1
	v_and_b32_e32 v2, 63, v16
	v_lshlrev_b32_e32 v3, 1, v16
	v_and_b32_e32 v4, 0x118, v20
	v_bitop3_b32 v241, v0, v8, s6 bitop3:0x36
	s_movk_i32 s6, 0xe0
	s_cselect_b32 s16, 0, 0
	s_lshl_b32 s23, s19, 18
	v_and_b32_e32 v5, 0xc0, v17
	v_bitop3_b32 v247, v0, v8, s6 bitop3:0x36
	v_cmp_gt_u32_e64 s[6:7], 32, v2
	v_and_or_b32 v2, v3, 32, v4
	s_add_u32 s14, s8, s14
	v_add3_u32 v248, v5, s16, v2
	s_addc_u32 s15, s9, s15
	v_readlane_b32 s16, v254, 41
	s_add_u32 s14, s16, s14
	v_readlane_b32 s16, v254, 42
	s_addc_u32 s15, s16, s15
	s_add_u32 s8, s8, s0
	s_addc_u32 s9, s9, s1
	v_or3_b32 v2, v23, v22, v18
	v_lshlrev_b32_e32 v2, 11, v2
	s_add_u32 s8, s88, s8
	v_or3_b32 v2, v2, v19, v21
	v_mov_b32_e32 v2, v245
	v_mov_b32_e32 v3, v1
	s_addc_u32 s9, s89, s9
	s_waitcnt vmcnt(0)
; __device__ __forceinline__ int v_rd_base(int lane) { return ((lane & 3) << 3) | (((lane >> 2) & 3) << 6) | (((lane >> 4) & 1) << 5) | (((lane >> 5) & 1) << 8); }
; __device__ __forceinline__ void attn_body256(const bf16_t* __restrict__ Qb, const bf16_t* __restrict__ Kh, const bf16_t* __restrict__ Vh,
;                                              bf16_t* Ob, int seq, unsigned char* lds, float lam, int MODE, bf16_t* Ab, const float* wsub) {
;     ...
;   float m_reg = -1e30f, l_reg = 0; f32x16 o[8] = {}; bf16x8 qr[8];
;   const bf16_t* Qw = Qb + (long)(wid * QBLK + r32) * LDQ + hi * 8;
; #pragma unroll
;   for (int d0 = 0; d0 < 8; ++d0) qr[d0] = *reinterpret_cast<const bf16x8*>(Qw + d0 * 16);
;   const int vb0 = (int)(uintptr_t)lds + v_rd_base(lane);
;   asm volatile("s_waitcnt vmcnt(0)" ::: "memory"); __syncthreads();
	v_bitop3_b32 v232, v0, v17, s26 bitop3:0x78
	v_lshl_add_u64 v[224:225], v[2:3], 1, s[8:9]
	v_or3_b32 v2, v24, v19, v21
	v_add_u32_e32 v2, 0x10000, v245
	v_mov_b32_e32 v16, v1
	v_mov_b32_e32 v17, v1
	v_bitop3_b32 v233, v0, v8, 32 bitop3:0x36
	v_bitop3_b32 v234, v0, v8, 64 bitop3:0x36
	v_lshl_add_u64 v[220:221], s[14:15], 0, v[12:13]
	v_lshl_add_u64 v[222:223], s[14:15], 0, v[6:7]
	v_lshl_add_u64 v[226:227], v[2:3], 1, s[8:9]
	v_mov_b32_e32 v2, v1
	v_mov_b32_e32 v4, v1
	v_mov_b32_e32 v5, v1
	v_mov_b32_e32 v6, v1
	v_mov_b32_e32 v7, v1
	v_mov_b32_e32 v8, v1
	v_mov_b32_e32 v9, v1
	v_mov_b32_e32 v10, v1
	v_mov_b32_e32 v12, v1
	v_mov_b32_e32 v13, v1
	v_mov_b32_e32 v14, v1
	v_mov_b32_e32 v15, v1
	v_mov_b64_e32 v[128:129], v[16:17]
	v_mov_b64_e32 v[112:113], v[16:17]
	v_mov_b64_e32 v[96:97], v[16:17]
	v_mov_b64_e32 v[80:81], v[16:17]
	v_mov_b64_e32 v[64:65], v[16:17]
	v_mov_b64_e32 v[48:49], v[16:17]
	v_mov_b64_e32 v[32:33], v[16:17]
	s_mov_b32 s13, 2
	v_lshlrev_b32_e32 v230, 8, v228
	v_lshl_add_u32 v238, v228, 2, s20
	v_mov_b32_e32 v250, 0
	v_mov_b32_e32 v249, 0xf149f2ca
	s_mov_b64 s[14:15], 0
	v_mov_b64_e32 v[126:127], v[14:15]
	v_mov_b64_e32 v[124:125], v[12:13]
	v_mov_b64_e32 v[122:123], v[10:11]
	v_mov_b64_e32 v[120:121], v[8:9]
	v_mov_b64_e32 v[118:119], v[6:7]
	v_mov_b64_e32 v[116:117], v[4:5]
	v_mov_b64_e32 v[114:115], v[2:3]
	v_mov_b64_e32 v[110:111], v[14:15]
	v_mov_b64_e32 v[108:109], v[12:13]
	v_mov_b64_e32 v[106:107], v[10:11]
	v_mov_b64_e32 v[104:105], v[8:9]
	v_mov_b64_e32 v[102:103], v[6:7]
	v_mov_b64_e32 v[100:101], v[4:5]
	v_mov_b64_e32 v[98:99], v[2:3]
	v_mov_b64_e32 v[94:95], v[14:15]
	v_mov_b64_e32 v[92:93], v[12:13]
	v_mov_b64_e32 v[90:91], v[10:11]
	v_mov_b64_e32 v[88:89], v[8:9]
	v_mov_b64_e32 v[86:87], v[6:7]
	v_mov_b64_e32 v[84:85], v[4:5]
	v_mov_b64_e32 v[82:83], v[2:3]
	v_mov_b64_e32 v[78:79], v[14:15]
	v_mov_b64_e32 v[76:77], v[12:13]
	v_mov_b64_e32 v[74:75], v[10:11]
	v_mov_b64_e32 v[72:73], v[8:9]
	v_mov_b64_e32 v[70:71], v[6:7]
	v_mov_b64_e32 v[68:69], v[4:5]
	v_mov_b64_e32 v[66:67], v[2:3]
	v_mov_b64_e32 v[62:63], v[14:15]
	v_mov_b64_e32 v[60:61], v[12:13]
	v_mov_b64_e32 v[58:59], v[10:11]
	v_mov_b64_e32 v[56:57], v[8:9]
	v_mov_b64_e32 v[54:55], v[6:7]
	v_mov_b64_e32 v[52:53], v[4:5]
	v_mov_b64_e32 v[50:51], v[2:3]
	v_mov_b64_e32 v[46:47], v[14:15]
	v_mov_b64_e32 v[44:45], v[12:13]
	v_mov_b64_e32 v[42:43], v[10:11]
	v_mov_b64_e32 v[40:41], v[8:9]
	v_mov_b64_e32 v[38:39], v[6:7]
	v_mov_b64_e32 v[36:37], v[4:5]
	v_mov_b64_e32 v[34:35], v[2:3]
	v_mov_b64_e32 v[30:31], v[14:15]
	v_mov_b64_e32 v[28:29], v[12:13]
	v_mov_b64_e32 v[26:27], v[10:11]
	v_mov_b64_e32 v[24:25], v[8:9]
	v_mov_b64_e32 v[22:23], v[6:7]
	v_mov_b64_e32 v[20:21], v[4:5]
	v_mov_b64_e32 v[18:19], v[2:3]
	v_and_b32_e32 v237, 15, v231
	v_bfe_u32 v240, v231, 4, 2
	v_and_b32_e32 v241, 7, v237
	v_lshlrev_b32_e32 v241, 4, v241
	v_lshlrev_b32_e32 v247, 4, v240
	v_xor_b32_e32 v232, v247, v241
	v_add_u32_e32 v247, 64, v247
	v_xor_b32_e32 v233, v247, v241
	v_lshlrev_b32_e32 v247, 8, v237
	v_add_u32_e32 v232, v232, v247
	v_add_u32_e32 v233, v233, v247
	v_and_b32_e32 v247, 1, v240
	v_lshlrev_b32_e32 v248, 7, v247
	v_lshrrev_b32_e32 v247, 1, v240
	v_lshl_add_u32 v248, v247, 11, v248
	v_bfe_u32 v247, v231, 2, 2
	v_lshl_add_u32 v248, v247, 5, v248
	v_and_b32_e32 v247, 3, v231
	v_lshl_add_u32 v248, v247, 3, v248
	v_mov_b32_e32 v249, 0xf149f2ca
	v_mov_b32_e32 v246, 0xf149f2ca
	v_mov_b32_e32 v250, 0
	v_mov_b32_e32 v234, 0
	s_movk_i32 s62, 0x7fff
	s_waitcnt vmcnt(0) lgkmcnt(0)
	s_barrier

; #define SBAR() __builtin_amdgcn_sched_barrier(0)
; __device__ __forceinline__ void partialSM(f32x16& p0, f32x16& p1, float& m_reg, float& mn, float& alpha) {
;     ...
;   for (int r = 0; r < 16; ++r) p0[r] = fmaf(p0[r], C, mnC); for (int r = 0; r < 16; ++r) p1[r] = fmaf(p1[r], C, mnC);
;   for (int r = 0; r < 16; ++r) p0[r] = __builtin_amdgcn_exp2f(p0[r]);
; }
; __device__ __forceinline__ void finishSM(f32x16& p0, f32x16& p1, float alpha, float& l_reg, bf16x8& pa0, bf16x8& pa1, bf16x8& pa2, bf16x8& pa3) {
;   for (int r = 0; r < 16; ++r) p1[r] = __builtin_amdgcn_exp2f(p1[r]);
;   float ps = 0; for (int r = 0; r < 16; ++r) ps += p0[r]; for (int r = 0; r < 16; ++r) ps += p1[r];
;   { auto rr = __builtin_amdgcn_permlane32_swap(__float_as_uint(ps), __float_as_uint(ps), false, false);
;     ps = __uint_as_float(rr[0]) + __uint_as_float(rr[1]); }
;   l_reg = l_reg * alpha + ps;
;     ...
;   PK4(p0, 0, pa0); PK4(p0, 8, pa1); PK4(p1, 0, pa2); PK4(p1, 8, pa3);
;     ...
; }
; template <int B> __device__ __forceinline__ void pv_reads(VFrag& f, int vb) {
;   constexpr int base = (B >> 2) * 16384 + (B & 3) * 512;
;   f.l0 = tr_read<base + 0 * 4096>(vb); f.h0 = tr_read<base + 0 * 4096 + 2048>(vb); f.l1 = tr_read<base + 1 * 4096>(vb); f.h1 = tr_read<base + 1 * 4096 + 2048>(vb);
;   f.l2 = tr_read<base + 2 * 4096>(vb); f.h2 = tr_read<base + 2 * 4096 + 2048>(vb); f.l3 = tr_read<base + 3 * 4096>(vb); f.h3 = tr_read<base + 3 * 4096 + 2048>(vb);
; }
; __device__ __forceinline__ void pv_mma(f32x16& od, const VFrag& f, bf16x8 pa0, bf16x8 pa1, bf16x8 pa2, bf16x8 pa3) {
;     ...
;   od = __builtin_amdgcn_mfma_f32_32x32x16_bf16(pa0, PKV(f.l0, f.h0), od, 0, 0, 0);
;   od = __builtin_amdgcn_mfma_f32_32x32x16_bf16(pa1, PKV(f.l1, f.h1), od, 0, 0, 0);
;   od = __builtin_amdgcn_mfma_f32_32x32x16_bf16(pa2, PKV(f.l2, f.h2), od, 0, 0, 0);
;   od = __builtin_amdgcn_mfma_f32_32x32x16_bf16(pa3, PKV(f.l3, f.h3), od, 0, 0, 0);
;     ...
; }
; __device__ __forceinline__ void pv_all(f32x16* o, int vb, bf16x8 pa0, bf16x8 pa1, bf16x8 pa2, bf16x8 pa3) {
;   VFrag fc, fn;
;   pv_reads<0>(fc, vb);
;   PV_STEP(0); PV_STEP(1); PV_STEP(2); PV_STEP(3); PV_STEP(4); PV_STEP(5); PV_STEP(6);
;   asm volatile("s_waitcnt lgkmcnt(0)" ::: "memory"); SBAR(); pv_mma(o[7], fc, pa0, pa1, pa2, pa3);
.Lat_noresc:
	v_mul_f32_e32 v198, 0xbe0293ee, v249
	v_mul_f32_e32 v199, 0xbe0293ee, v246
	v_fmamk_f32 v130, v130, 0x3e0293ee, v198
	v_fmamk_f32 v131, v131, 0x3e0293ee, v198
	v_fmamk_f32 v132, v132, 0x3e0293ee, v198
	v_fmamk_f32 v133, v133, 0x3e0293ee, v198
	v_fmamk_f32 v134, v134, 0x3e0293ee, v199
	v_fmamk_f32 v135, v135, 0x3e0293ee, v199
	v_fmamk_f32 v136, v136, 0x3e0293ee, v199
	v_fmamk_f32 v137, v137, 0x3e0293ee, v199
	v_fmamk_f32 v138, v138, 0x3e0293ee, v198
	v_fmamk_f32 v139, v139, 0x3e0293ee, v198
	v_fmamk_f32 v140, v140, 0x3e0293ee, v198
	v_fmamk_f32 v141, v141, 0x3e0293ee, v198
	v_fmamk_f32 v142, v142, 0x3e0293ee, v199
	v_fmamk_f32 v143, v143, 0x3e0293ee, v199
	v_fmamk_f32 v144, v144, 0x3e0293ee, v199
	v_fmamk_f32 v145, v145, 0x3e0293ee, v199
	v_fmamk_f32 v146, v146, 0x3e0293ee, v198
	v_fmamk_f32 v147, v147, 0x3e0293ee, v198
	v_fmamk_f32 v148, v148, 0x3e0293ee, v198
	v_fmamk_f32 v149, v149, 0x3e0293ee, v198
	v_fmamk_f32 v150, v150, 0x3e0293ee, v199
	v_fmamk_f32 v151, v151, 0x3e0293ee, v199
	v_fmamk_f32 v152, v152, 0x3e0293ee, v199
	v_fmamk_f32 v153, v153, 0x3e0293ee, v199
	v_fmamk_f32 v154, v154, 0x3e0293ee, v198
	v_fmamk_f32 v155, v155, 0x3e0293ee, v198
	v_fmamk_f32 v156, v156, 0x3e0293ee, v198
	v_fmamk_f32 v157, v157, 0x3e0293ee, v198
	v_fmamk_f32 v158, v158, 0x3e0293ee, v199
	v_fmamk_f32 v159, v159, 0x3e0293ee, v199
	v_fmamk_f32 v160, v160, 0x3e0293ee, v199
	v_fmamk_f32 v161, v161, 0x3e0293ee, v199
	v_exp_f32_e32 v130, v130
	v_exp_f32_e32 v131, v131
	v_exp_f32_e32 v132, v132
	v_exp_f32_e32 v133, v133
	v_exp_f32_e32 v134, v134
	v_exp_f32_e32 v135, v135
	v_exp_f32_e32 v136, v136
	v_exp_f32_e32 v137, v137
	v_exp_f32_e32 v138, v138
	v_exp_f32_e32 v139, v139
	v_exp_f32_e32 v140, v140
	v_exp_f32_e32 v141, v141
	v_exp_f32_e32 v142, v142
	v_exp_f32_e32 v143, v143
	v_exp_f32_e32 v144, v144
	v_exp_f32_e32 v145, v145
	v_exp_f32_e32 v146, v146
	v_exp_f32_e32 v147, v147
	v_exp_f32_e32 v148, v148
	v_exp_f32_e32 v149, v149
	v_exp_f32_e32 v150, v150
	v_exp_f32_e32 v151, v151
	v_exp_f32_e32 v152, v152
	v_exp_f32_e32 v153, v153
	v_exp_f32_e32 v154, v154
	v_exp_f32_e32 v155, v155
	v_exp_f32_e32 v156, v156
	v_exp_f32_e32 v157, v157
	v_exp_f32_e32 v158, v158
	v_exp_f32_e32 v159, v159
	v_exp_f32_e32 v160, v160
	v_exp_f32_e32 v161, v161
	v_add_f32_e32 v194, v130, v131
	v_add_f32_e32 v194, v194, v132
	v_add_f32_e32 v194, v194, v133
	v_add_f32_e32 v194, v194, v138
	v_add_f32_e32 v194, v194, v139
	v_add_f32_e32 v194, v194, v140
	v_add_f32_e32 v194, v194, v141
	v_add_f32_e32 v194, v194, v146
	v_add_f32_e32 v194, v194, v147
	v_add_f32_e32 v194, v194, v148
	v_add_f32_e32 v194, v194, v149
	v_add_f32_e32 v194, v194, v154
	v_add_f32_e32 v194, v194, v155
	v_add_f32_e32 v194, v194, v156
	v_add_f32_e32 v194, v194, v157
	v_add_f32_e32 v195, v134, v135
	v_add_f32_e32 v195, v195, v136
	v_add_f32_e32 v195, v195, v137
	v_add_f32_e32 v195, v195, v142
	v_add_f32_e32 v195, v195, v143
	v_add_f32_e32 v195, v195, v144
	v_add_f32_e32 v195, v195, v145
	v_add_f32_e32 v195, v195, v150
	v_add_f32_e32 v195, v195, v151
	v_add_f32_e32 v195, v195, v152
	v_add_f32_e32 v195, v195, v153
	v_add_f32_e32 v195, v195, v158
	v_add_f32_e32 v195, v195, v159
	v_add_f32_e32 v195, v195, v160
	v_add_f32_e32 v195, v195, v161
	v_fma_f32 v250, v250, v236, v194
	v_fma_f32 v234, v234, v240, v195
	v_cvt_pk_bf16_f32 v130, v130, v131
	v_cvt_pk_bf16_f32 v131, v132, v133
	v_cvt_pk_bf16_f32 v132, v138, v139
	v_cvt_pk_bf16_f32 v133, v140, v141
	v_cvt_pk_bf16_f32 v134, v134, v135
	v_cvt_pk_bf16_f32 v135, v136, v137
	v_cvt_pk_bf16_f32 v136, v142, v143
	v_cvt_pk_bf16_f32 v137, v144, v145
	v_cvt_pk_bf16_f32 v138, v146, v147
	v_cvt_pk_bf16_f32 v139, v148, v149
	v_cvt_pk_bf16_f32 v140, v154, v155
	v_cvt_pk_bf16_f32 v141, v156, v157
	v_cvt_pk_bf16_f32 v142, v150, v151
	v_cvt_pk_bf16_f32 v143, v152, v153
	v_cvt_pk_bf16_f32 v144, v158, v159
	v_cvt_pk_bf16_f32 v145, v160, v161
	ds_read_b64_tr_b16 v[146:147], v244
	ds_read_b64_tr_b16 v[148:149], v244 offset:4096
	ds_read_b64_tr_b16 v[150:151], v244 offset:8192
	ds_read_b64_tr_b16 v[152:153], v244 offset:12288
	ds_read_b64_tr_b16 v[154:155], v244 offset:256
	ds_read_b64_tr_b16 v[156:157], v244 offset:4352
	ds_read_b64_tr_b16 v[158:159], v244 offset:8448
	ds_read_b64_tr_b16 v[160:161], v244 offset:12544
	ds_read_b64_tr_b16 v[194:195], v244 offset:512
	ds_read_b64_tr_b16 v[196:197], v244 offset:4608
	ds_read_b64_tr_b16 v[198:199], v244 offset:8704
	ds_read_b64_tr_b16 v[200:201], v244 offset:12800
	s_waitcnt lgkmcnt(8)
	v_mfma_f32_16x16x32_bf16 v[2:5], v[146:149], v[130:133], v[2:5]
	v_mfma_f32_16x16x32_bf16 v[6:9], v[146:149], v[134:137], v[6:9]
	v_mfma_f32_16x16x32_bf16 v[2:5], v[150:153], v[138:141], v[2:5]
	v_mfma_f32_16x16x32_bf16 v[6:9], v[150:153], v[142:145], v[6:9]
	ds_read_b64_tr_b16 v[146:147], v244 offset:768
	ds_read_b64_tr_b16 v[148:149], v244 offset:4864
	ds_read_b64_tr_b16 v[150:151], v244 offset:8960
	ds_read_b64_tr_b16 v[152:153], v244 offset:13056
	s_waitcnt lgkmcnt(8)
	v_mfma_f32_16x16x32_bf16 v[10:13], v[154:157], v[130:133], v[10:13]
	v_mfma_f32_16x16x32_bf16 v[14:17], v[154:157], v[134:137], v[14:17]
	v_mfma_f32_16x16x32_bf16 v[10:13], v[158:161], v[138:141], v[10:13]
	v_mfma_f32_16x16x32_bf16 v[14:17], v[158:161], v[142:145], v[14:17]
	ds_read_b64_tr_b16 v[154:155], v244 offset:1024
	ds_read_b64_tr_b16 v[156:157], v244 offset:5120
	ds_read_b64_tr_b16 v[158:159], v244 offset:9216
	ds_read_b64_tr_b16 v[160:161], v244 offset:13312
	s_waitcnt lgkmcnt(8)
; #define SBAR() __builtin_amdgcn_sched_barrier(0)
; #define PV_STEP(B) do { pv_reads<(B) + 1>(fn, vb); asm volatile("s_waitcnt lgkmcnt(8)" ::: "memory"); SBAR(); pv_mma(o[B], fc, pa0, pa1, pa2, pa3); SBAR(); fc = fn; } while (0)
; template <int B> __device__ __forceinline__ void pv_reads(VFrag& f, int vb) {
;   constexpr int base = (B >> 2) * 16384 + (B & 3) * 512;
;   f.l0 = tr_read<base + 0 * 4096>(vb); f.h0 = tr_read<base + 0 * 4096 + 2048>(vb); f.l1 = tr_read<base + 1 * 4096>(vb); f.h1 = tr_read<base + 1 * 4096 + 2048>(vb);
;   f.l2 = tr_read<base + 2 * 4096>(vb); f.h2 = tr_read<base + 2 * 4096 + 2048>(vb); f.l3 = tr_read<base + 3 * 4096>(vb); f.h3 = tr_read<base + 3 * 4096 + 2048>(vb);
; }
; __device__ __forceinline__ void pv_mma(f32x16& od, const VFrag& f, bf16x8 pa0, bf16x8 pa1, bf16x8 pa2, bf16x8 pa3) {
;     ...
;   od = __builtin_amdgcn_mfma_f32_32x32x16_bf16(pa0, PKV(f.l0, f.h0), od, 0, 0, 0);
;   od = __builtin_amdgcn_mfma_f32_32x32x16_bf16(pa1, PKV(f.l1, f.h1), od, 0, 0, 0);
;   od = __builtin_amdgcn_mfma_f32_32x32x16_bf16(pa2, PKV(f.l2, f.h2), od, 0, 0, 0);
;   od = __builtin_amdgcn_mfma_f32_32x32x16_bf16(pa3, PKV(f.l3, f.h3), od, 0, 0, 0);
;     ...
; }
; __device__ __forceinline__ void pv_all(f32x16* o, int vb, bf16x8 pa0, bf16x8 pa1, bf16x8 pa2, bf16x8 pa3) {
;   VFrag fc, fn;
;   pv_reads<0>(fc, vb);
;   PV_STEP(0); PV_STEP(1); PV_STEP(2); PV_STEP(3); PV_STEP(4); PV_STEP(5); PV_STEP(6);
;   asm volatile("s_waitcnt lgkmcnt(0)" ::: "memory"); SBAR(); pv_mma(o[7], fc, pa0, pa1, pa2, pa3);
; }
; __device__ __forceinline__ void attn_body256(const bf16_t* __restrict__ Qb, const bf16_t* __restrict__ Kh, const bf16_t* __restrict__ Vh,
;                                              bf16_t* Ob, int seq, unsigned char* lds, float lam, int MODE, bf16_t* Ab, const float* wsub) {
;     ...
;     asm volatile("s_waitcnt vmcnt(0)" ::: "memory"); __syncthreads();
	v_mfma_f32_16x16x32_bf16 v[114:117], v[194:197], v[130:133], v[114:117]
	v_mfma_f32_16x16x32_bf16 v[118:121], v[194:197], v[134:137], v[118:121]
	v_mfma_f32_16x16x32_bf16 v[114:117], v[198:201], v[138:141], v[114:117]
	v_mfma_f32_16x16x32_bf16 v[118:121], v[198:201], v[142:145], v[118:121]
	ds_read_b64_tr_b16 v[194:195], v244 offset:1280
	ds_read_b64_tr_b16 v[196:197], v244 offset:5376
	ds_read_b64_tr_b16 v[198:199], v244 offset:9472
	ds_read_b64_tr_b16 v[200:201], v244 offset:13568
	s_waitcnt lgkmcnt(8)
	v_mfma_f32_16x16x32_bf16 v[122:125], v[146:149], v[130:133], v[122:125]
	v_mfma_f32_16x16x32_bf16 v[126:129], v[146:149], v[134:137], v[126:129]
	v_mfma_f32_16x16x32_bf16 v[122:125], v[150:153], v[138:141], v[122:125]
	v_mfma_f32_16x16x32_bf16 v[126:129], v[150:153], v[142:145], v[126:129]
	ds_read_b64_tr_b16 v[146:147], v244 offset:1536
	ds_read_b64_tr_b16 v[148:149], v244 offset:5632
	ds_read_b64_tr_b16 v[150:151], v244 offset:9728
	ds_read_b64_tr_b16 v[152:153], v244 offset:13824
	s_waitcnt lgkmcnt(8)
	v_mfma_f32_16x16x32_bf16 v[98:101], v[154:157], v[130:133], v[98:101]
	v_mfma_f32_16x16x32_bf16 v[102:105], v[154:157], v[134:137], v[102:105]
	v_mfma_f32_16x16x32_bf16 v[98:101], v[158:161], v[138:141], v[98:101]
	v_mfma_f32_16x16x32_bf16 v[102:105], v[158:161], v[142:145], v[102:105]
	ds_read_b64_tr_b16 v[154:155], v244 offset:1792
	ds_read_b64_tr_b16 v[156:157], v244 offset:5888
	ds_read_b64_tr_b16 v[158:159], v244 offset:9984
	ds_read_b64_tr_b16 v[160:161], v244 offset:14080
	s_waitcnt lgkmcnt(8)
	v_mfma_f32_16x16x32_bf16 v[106:109], v[194:197], v[130:133], v[106:109]
	v_mfma_f32_16x16x32_bf16 v[110:113], v[194:197], v[134:137], v[110:113]
	v_mfma_f32_16x16x32_bf16 v[106:109], v[198:201], v[138:141], v[106:109]
	v_mfma_f32_16x16x32_bf16 v[110:113], v[198:201], v[142:145], v[110:113]
	ds_read_b64_tr_b16 v[194:195], v244 offset:16384
	ds_read_b64_tr_b16 v[196:197], v244 offset:20480
	ds_read_b64_tr_b16 v[198:199], v244 offset:24576
	ds_read_b64_tr_b16 v[200:201], v244 offset:28672
	s_waitcnt lgkmcnt(8)
	v_mfma_f32_16x16x32_bf16 v[82:85], v[146:149], v[130:133], v[82:85]
	v_mfma_f32_16x16x32_bf16 v[86:89], v[146:149], v[134:137], v[86:89]
	v_mfma_f32_16x16x32_bf16 v[82:85], v[150:153], v[138:141], v[82:85]
	v_mfma_f32_16x16x32_bf16 v[86:89], v[150:153], v[142:145], v[86:89]
	ds_read_b64_tr_b16 v[146:147], v244 offset:16640
	ds_read_b64_tr_b16 v[148:149], v244 offset:20736
	ds_read_b64_tr_b16 v[150:151], v244 offset:24832
	ds_read_b64_tr_b16 v[152:153], v244 offset:28928
	s_waitcnt lgkmcnt(8)
	v_mfma_f32_16x16x32_bf16 v[90:93], v[154:157], v[130:133], v[90:93]
	v_mfma_f32_16x16x32_bf16 v[94:97], v[154:157], v[134:137], v[94:97]
	v_mfma_f32_16x16x32_bf16 v[90:93], v[158:161], v[138:141], v[90:93]
	v_mfma_f32_16x16x32_bf16 v[94:97], v[158:161], v[142:145], v[94:97]
	ds_read_b64_tr_b16 v[154:155], v244 offset:16896
	ds_read_b64_tr_b16 v[156:157], v244 offset:20992
	ds_read_b64_tr_b16 v[158:159], v244 offset:25088
	ds_read_b64_tr_b16 v[160:161], v244 offset:29184
	s_waitcnt lgkmcnt(8)
	v_mfma_f32_16x16x32_bf16 v[66:69], v[194:197], v[130:133], v[66:69]
	v_mfma_f32_16x16x32_bf16 v[70:73], v[194:197], v[134:137], v[70:73]
	v_mfma_f32_16x16x32_bf16 v[66:69], v[198:201], v[138:141], v[66:69]
	v_mfma_f32_16x16x32_bf16 v[70:73], v[198:201], v[142:145], v[70:73]
	ds_read_b64_tr_b16 v[194:195], v244 offset:17152
	ds_read_b64_tr_b16 v[196:197], v244 offset:21248
	ds_read_b64_tr_b16 v[198:199], v244 offset:25344
	ds_read_b64_tr_b16 v[200:201], v244 offset:29440
	s_waitcnt lgkmcnt(8)
	v_mfma_f32_16x16x32_bf16 v[74:77], v[146:149], v[130:133], v[74:77]
	v_mfma_f32_16x16x32_bf16 v[78:81], v[146:149], v[134:137], v[78:81]
	v_mfma_f32_16x16x32_bf16 v[74:77], v[150:153], v[138:141], v[74:77]
	v_mfma_f32_16x16x32_bf16 v[78:81], v[150:153], v[142:145], v[78:81]
	ds_read_b64_tr_b16 v[146:147], v244 offset:17408
	ds_read_b64_tr_b16 v[148:149], v244 offset:21504
	ds_read_b64_tr_b16 v[150:151], v244 offset:25600
	ds_read_b64_tr_b16 v[152:153], v244 offset:29696
	s_waitcnt lgkmcnt(8)
	v_mfma_f32_16x16x32_bf16 v[50:53], v[154:157], v[130:133], v[50:53]
	v_mfma_f32_16x16x32_bf16 v[54:57], v[154:157], v[134:137], v[54:57]
	v_mfma_f32_16x16x32_bf16 v[50:53], v[158:161], v[138:141], v[50:53]
	v_mfma_f32_16x16x32_bf16 v[54:57], v[158:161], v[142:145], v[54:57]
	ds_read_b64_tr_b16 v[154:155], v244 offset:17664
	ds_read_b64_tr_b16 v[156:157], v244 offset:21760
	ds_read_b64_tr_b16 v[158:159], v244 offset:25856
	ds_read_b64_tr_b16 v[160:161], v244 offset:29952
	s_waitcnt lgkmcnt(8)
	v_mfma_f32_16x16x32_bf16 v[58:61], v[194:197], v[130:133], v[58:61]
	v_mfma_f32_16x16x32_bf16 v[62:65], v[194:197], v[134:137], v[62:65]
	v_mfma_f32_16x16x32_bf16 v[58:61], v[198:201], v[138:141], v[58:61]
	v_mfma_f32_16x16x32_bf16 v[62:65], v[198:201], v[142:145], v[62:65]
	ds_read_b64_tr_b16 v[194:195], v244 offset:17920
	ds_read_b64_tr_b16 v[196:197], v244 offset:22016
	ds_read_b64_tr_b16 v[198:199], v244 offset:26112
	ds_read_b64_tr_b16 v[200:201], v244 offset:30208
	s_waitcnt lgkmcnt(8)
	v_mfma_f32_16x16x32_bf16 v[34:37], v[146:149], v[130:133], v[34:37]
	v_mfma_f32_16x16x32_bf16 v[38:41], v[146:149], v[134:137], v[38:41]
	v_mfma_f32_16x16x32_bf16 v[34:37], v[150:153], v[138:141], v[34:37]
	v_mfma_f32_16x16x32_bf16 v[38:41], v[150:153], v[142:145], v[38:41]
	ds_read_b64_tr_b16 v[146:147], v244 offset:18176
	ds_read_b64_tr_b16 v[148:149], v244 offset:22272
	ds_read_b64_tr_b16 v[150:151], v244 offset:26368
	ds_read_b64_tr_b16 v[152:153], v244 offset:30464
	s_waitcnt lgkmcnt(8)
	v_mfma_f32_16x16x32_bf16 v[42:45], v[154:157], v[130:133], v[42:45]
	v_mfma_f32_16x16x32_bf16 v[46:49], v[154:157], v[134:137], v[46:49]
	v_mfma_f32_16x16x32_bf16 v[42:45], v[158:161], v[138:141], v[42:45]
	v_mfma_f32_16x16x32_bf16 v[46:49], v[158:161], v[142:145], v[46:49]
	s_waitcnt lgkmcnt(4)
	v_mfma_f32_16x16x32_bf16 v[18:21], v[194:197], v[130:133], v[18:21]
	v_mfma_f32_16x16x32_bf16 v[22:25], v[194:197], v[134:137], v[22:25]
	v_mfma_f32_16x16x32_bf16 v[18:21], v[198:201], v[138:141], v[18:21]
	v_mfma_f32_16x16x32_bf16 v[22:25], v[198:201], v[142:145], v[22:25]
	s_waitcnt lgkmcnt(0)
	v_mfma_f32_16x16x32_bf16 v[26:29], v[146:149], v[130:133], v[26:29]
	v_mfma_f32_16x16x32_bf16 v[30:33], v[146:149], v[134:137], v[30:33]
	v_mfma_f32_16x16x32_bf16 v[26:29], v[150:153], v[138:141], v[26:29]
	v_mfma_f32_16x16x32_bf16 v[30:33], v[150:153], v[142:145], v[30:33]
	s_waitcnt vmcnt(0)
	s_barrier
; __device__ __forceinline__ bf16_t f2bf(float x) { return (bf16_t)(cvt_pk_bf16(x, x) & 0xffffu); }
; __device__ __forceinline__ float bf2f(bf16_t b) { return __uint_as_float(((unsigned)b) << 16); }
; __device__ __forceinline__ int crow(int r, int hi) { return (r & 3) + 8 * (r >> 2) + 4 * hi; }
; __device__ __forceinline__ int crow(int r, int hi) { return (r & 3) + 8 * (r >> 2) + 4 * hi; }
; __device__ __forceinline__ void attn_body256(const bf16_t* __restrict__ Qb, const bf16_t* __restrict__ Kh, const bf16_t* __restrict__ Vh,
;                                              bf16_t* Ob, int seq, unsigned char* lds, float lam, int MODE, bf16_t* Ab, const float* wsub) {
;     ...
;     asm volatile("s_waitcnt vmcnt(0)" ::: "memory"); __syncthreads();
;     if (j + 2 < NT) A2_DMA(j + 2, b);
;   }
;   if (hi == 0) li_l[r32] = l_reg; asm volatile("s_waitcnt lgkmcnt(0)" ::: "memory");
;   float rli[16];
; #pragma unroll
;   for (int r = 0; r < 16; ++r) rli[r] = __builtin_amdgcn_rcpf(li_l[crow(r, hi)]);
;   bf16_t* Ow = Ob + (long)(wid * QBLK) * LDO;
;   if (MODE == 0) {
; #pragma unroll
;     for (int r = 0; r < 16; ++r) { const int orow = crow(r, hi);
; #pragma unroll
;       for (int d0 = 0; d0 < 8; ++d0) Ow[(long)orow * LDO + d0 * 32 + r32] = f2bf(o[d0][r] * rli[r]); }
;   } else {
;     bf16_t* Aw = Ab + (long)(wid * QBLK) * LDO;
;     float wv[8];
; #pragma unroll
;     for (int d0 = 0; d0 < 8; ++d0) wv[d0] = wsub[d0 * 32 + r32] * (1.f - LAMBDA_INIT);
; #pragma unroll
;     for (int r = 0; r < 16; ++r) { const int orow = crow(r, hi); float ss = 0.f;
; #pragma unroll
;       for (int d0 = 0; d0 < 8; ++d0) { const float v = bf2f(Ow[(long)orow * LDO + d0 * 32 + r32]) - lam * (o[d0][r] * rli[r]); o[d0][r] = v; ss += v * v; }
	s_cmp_ge_u32 s13, s19
	s_cbranch_scc1 .Lat_nodma
	s_lshl_b32 s8, s25, 15
	s_add_i32 s9, s22, s24
	v_lshl_add_u64 v[194:195], v[220:221], 0, s[14:15]
	s_mov_b32 m0, s9
	s_add_i32 s8, s21, s8
	global_load_lds_dwordx4 v[194:195], off
	v_lshl_add_u64 v[194:195], v[224:225], 0, s[14:15]
	s_add_i32 s16, s8, 0x4000
	v_lshl_add_u64 v[196:197], v[194:195], 0, s[54:55]
	s_mov_b32 m0, s8
	v_lshl_add_u64 v[194:195], v[194:195], 0, s[4:5]
	global_load_lds_dwordx4 v[196:197], off
	s_mov_b32 m0, s16
	s_nop 0
	global_load_lds_dwordx4 v[194:195], off
	v_lshl_add_u64 v[194:195], v[222:223], 0, s[14:15]
	s_add_i32 m0, s9, 0x2000
	s_nop 0
	global_load_lds_dwordx4 v[194:195], off
	v_lshl_add_u64 v[194:195], v[226:227], 0, s[14:15]
	v_lshl_add_u64 v[196:197], v[194:195], 0, s[54:55]
	s_add_i32 m0, s8, 0x2000
	v_lshl_add_u64 v[194:195], v[194:195], 0, s[4:5]
	global_load_lds_dwordx4 v[196:197], off
	s_add_i32 m0, s8, 0x6000
	s_nop 0
	global_load_lds_dwordx4 v[194:195], off
.Lat_nodma:
	s_add_u32 s14, s14, 0x40000
	s_addc_u32 s15, s15, 0
	s_add_i32 s13, s13, 1
	s_cmp_eq_u32 s23, s14
	s_cbranch_scc0 .Lat_top
	v_mov_b32_e32 v196, v250
	v_mov_b32_e32 v197, v234
	s_nop 1
	v_permlane32_swap_b32_e32 v250, v196
	v_permlane32_swap_b32_e32 v234, v197
	v_add_f32_e32 v250, v250, v196
	v_add_f32_e32 v234, v234, v197
	v_mov_b32_e32 v196, v250
	v_mov_b32_e32 v197, v234
	s_nop 1
	v_permlane16_swap_b32_e32 v250, v196
	v_permlane16_swap_b32_e32 v234, v197
	v_add_f32_e32 v250, v250, v196
	v_add_f32_e32 v234, v234, v197
	v_rcp_f32_e32 v198, v250
	v_rcp_f32_e32 v199, v234
	v_and_b32_e32 v202, 15, v231
	v_lshlrev_b32_e32 v202, 12, v202
	v_bfe_u32 v203, v231, 4, 2
	v_lshlrev_b32_e32 v210, 4, v203
	v_lshl_add_u32 v202, v203, 3, v202
	v_mov_b32_e32 v203, 0
	v_mov_b32_e32 v208, 0x10000
	v_mov_b32_e32 v209, 0
	s_lshl_b64 s[8:9], s[10:11], 1
	s_add_u32 s6, s92, s8
	s_addc_u32 s7, s93, s9
	s_add_u32 s10, s6, s0
	s_addc_u32 s11, s7, s1
	s_ashr_i32 s13, s12, 31
	s_lshl_b64 s[6:7], s[12:13], 12
	s_add_u32 s6, s10, s6
	s_addc_u32 s7, s11, s7
	s_cmp_lg_u32 s2, 0
	s_mov_b64 s[10:11], -1
	v_lshl_add_u64 v[194:195], s[6:7], 0, v[202:203]
	v_lshl_add_u64 v[196:197], v[194:195], 0, v[208:209]
	s_cmp_lg_u32 s2, 0
	s_cbranch_scc0 .Lat_e682
	s_lshl_b64 s[10:11], s[12:13], 11
	s_add_u32 s2, s76, s8
	s_addc_u32 s8, s77, s9
	v_readlane_b32 s72, v252, 22
	v_readlane_b32 s76, v252, 26
	v_readlane_b32 s77, v252, 27
	v_readlane_b32 s78, v252, 28
	v_readlane_b32 s79, v252, 29
	v_readlane_b32 s80, v252, 30
	v_readlane_b32 s81, v252, 31
	v_readlane_b32 s82, v252, 32
	v_readlane_b32 s83, v252, 33
	v_readlane_b32 s84, v252, 34
	v_readlane_b32 s85, v252, 35
	s_mov_b64 s[20:21], s[76:77]
	s_mov_b64 s[28:29], s[84:85]
	s_add_u32 s2, s2, s0
	s_addc_u32 s8, s8, s1
	s_lshl_b64 s[0:1], s[10:11], 1
	s_add_u32 s0, s2, s0
	s_addc_u32 s1, s8, s1
	s_mov_b32 s2, 0x3b800000
	v_readlane_b32 s73, v252, 23
	v_readlane_b32 s74, v252, 24
	v_readlane_b32 s75, v252, 25
	v_readlane_b32 s72, v254, 62
	v_readlane_b32 s74, v254, 53
	s_mov_b64 s[22:23], s[78:79]
	s_mov_b64 s[24:25], s[80:81]
	s_mov_b64 s[26:27], s[82:83]
	v_readlane_b32 s80, v255, 2
	v_readlane_b32 s78, v255, 0
	v_readlane_b32 s84, v254, 60
	v_readlane_b32 s82, v254, 58
	v_readlane_b32 s76, v254, 55
	v_readlane_b32 s86, v252, 36
	v_readlane_b32 s87, v252, 37
	v_readlane_b32 s73, v254, 63
	v_readlane_b32 s75, v254, 54
	v_readlane_b32 s81, v255, 3
	v_readlane_b32 s79, v255, 1
	v_readlane_b32 s85, v254, 61
	v_readlane_b32 s83, v254, 59
	v_readlane_b32 s77, v254, 56
	s_mov_b64 s[10:11], 0
	v_lshl_add_u64 v[204:205], s[0:1], 0, v[202:203]
	v_lshl_add_u64 v[206:207], v[204:205], 0, v[208:209]
	global_load_dwordx2 v[130:131], v[194:195], off
	global_load_dwordx2 v[132:133], v[194:195], off offset:32
	global_load_dwordx2 v[134:135], v[194:195], off offset:64
	global_load_dwordx2 v[136:137], v[194:195], off offset:96
	global_load_dwordx2 v[138:139], v[194:195], off offset:128
	global_load_dwordx2 v[140:141], v[194:195], off offset:160
	global_load_dwordx2 v[142:143], v[194:195], off offset:192
	global_load_dwordx2 v[144:145], v[194:195], off offset:224
	global_load_dwordx2 v[146:147], v[194:195], off offset:256
	global_load_dwordx2 v[148:149], v[194:195], off offset:288
	global_load_dwordx2 v[150:151], v[194:195], off offset:320
	global_load_dwordx2 v[152:153], v[194:195], off offset:352
	global_load_dwordx2 v[154:155], v[194:195], off offset:384
	global_load_dwordx2 v[156:157], v[194:195], off offset:416
	global_load_dwordx2 v[158:159], v[194:195], off offset:448
	global_load_dwordx2 v[160:161], v[194:195], off offset:480
	global_load_dwordx2 v[162:163], v[196:197], off
	global_load_dwordx2 v[164:165], v[196:197], off offset:32
	global_load_dwordx2 v[166:167], v[196:197], off offset:64
	global_load_dwordx2 v[168:169], v[196:197], off offset:96
	global_load_dwordx2 v[170:171], v[196:197], off offset:128
	global_load_dwordx2 v[172:173], v[196:197], off offset:160
	global_load_dwordx2 v[174:175], v[196:197], off offset:192
	global_load_dwordx2 v[176:177], v[196:197], off offset:224
	global_load_dwordx2 v[178:179], v[196:197], off offset:256
	global_load_dwordx2 v[180:181], v[196:197], off offset:288
	global_load_dwordx2 v[182:183], v[196:197], off offset:320
	global_load_dwordx2 v[184:185], v[196:197], off offset:352
	global_load_dwordx2 v[186:187], v[196:197], off offset:384
	global_load_dwordx2 v[188:189], v[196:197], off offset:416
	global_load_dwordx2 v[190:191], v[196:197], off offset:448
	global_load_dwordx2 v[192:193], v[196:197], off offset:480
	v_mov_b32_e32 v200, 0
	v_mov_b32_e32 v201, 0
	s_waitcnt vmcnt(31)
; __device__ __forceinline__ float bf2f(bf16_t b) { return __uint_as_float(((unsigned)b) << 16); }
; __device__ __forceinline__ int crow(int r, int hi) { return (r & 3) + 8 * (r >> 2) + 4 * hi; }
; __device__ __forceinline__ int crow(int r, int hi) { return (r & 3) + 8 * (r >> 2) + 4 * hi; }
; __device__ __forceinline__ void attn_body256(const bf16_t* __restrict__ Qb, const bf16_t* __restrict__ Kh, const bf16_t* __restrict__ Vh,
;                                              bf16_t* Ob, int seq, unsigned char* lds, float lam, int MODE, bf16_t* Ab, const float* wsub) {
;     ...
;     for (int r = 0; r < 16; ++r) { const int orow = crow(r, hi); float ss = 0.f;
; #pragma unroll
;       for (int d0 = 0; d0 < 8; ++d0) { const float v = bf2f(Ow[(long)orow * LDO + d0 * 32 + r32]) - lam * (o[d0][r] * rli[r]); o[d0][r] = v; ss += v * v; }
	v_lshlrev_b32_e32 v211, 16, v130
	v_mul_f32_e32 v2, v2, v198
	v_fma_f32 v2, -v218, v2, v211
	v_fmac_f32_e32 v200, v2, v2
	v_and_b32_e32 v211, 0xffff0000, v130
	v_mul_f32_e32 v3, v3, v198
	v_fma_f32 v3, -v218, v3, v211
	v_fmac_f32_e32 v200, v3, v3
	v_lshlrev_b32_e32 v211, 16, v131
	v_mul_f32_e32 v4, v4, v198
	v_fma_f32 v4, -v218, v4, v211
	v_fmac_f32_e32 v200, v4, v4
	v_and_b32_e32 v211, 0xffff0000, v131
	v_mul_f32_e32 v5, v5, v198
	v_fma_f32 v5, -v218, v5, v211
	v_fmac_f32_e32 v200, v5, v5
	s_waitcnt vmcnt(30)
	v_lshlrev_b32_e32 v211, 16, v132
	v_mul_f32_e32 v10, v10, v198
	v_fma_f32 v10, -v218, v10, v211
	v_fmac_f32_e32 v200, v10, v10
	v_and_b32_e32 v211, 0xffff0000, v132
	v_mul_f32_e32 v11, v11, v198
	v_fma_f32 v11, -v218, v11, v211
	v_fmac_f32_e32 v200, v11, v11
	v_lshlrev_b32_e32 v211, 16, v133
	v_mul_f32_e32 v12, v12, v198
	v_fma_f32 v12, -v218, v12, v211
	v_fmac_f32_e32 v200, v12, v12
	v_and_b32_e32 v211, 0xffff0000, v133
	v_mul_f32_e32 v13, v13, v198
	v_fma_f32 v13, -v218, v13, v211
	v_fmac_f32_e32 v200, v13, v13
	s_waitcnt vmcnt(29)
	v_lshlrev_b32_e32 v211, 16, v134
	v_mul_f32_e32 v114, v114, v198
	v_fma_f32 v114, -v218, v114, v211
	v_fmac_f32_e32 v200, v114, v114
	v_and_b32_e32 v211, 0xffff0000, v134
	v_mul_f32_e32 v115, v115, v198
	v_fma_f32 v115, -v218, v115, v211
	v_fmac_f32_e32 v200, v115, v115
	v_lshlrev_b32_e32 v211, 16, v135
	v_mul_f32_e32 v116, v116, v198
	v_fma_f32 v116, -v218, v116, v211
	v_fmac_f32_e32 v200, v116, v116
	v_and_b32_e32 v211, 0xffff0000, v135
	v_mul_f32_e32 v117, v117, v198
	v_fma_f32 v117, -v218, v117, v211
	v_fmac_f32_e32 v200, v117, v117
	s_waitcnt vmcnt(28)
	v_lshlrev_b32_e32 v211, 16, v136
	v_mul_f32_e32 v122, v122, v198
	v_fma_f32 v122, -v218, v122, v211
	v_fmac_f32_e32 v200, v122, v122
	v_and_b32_e32 v211, 0xffff0000, v136
	v_mul_f32_e32 v123, v123, v198
	v_fma_f32 v123, -v218, v123, v211
	v_fmac_f32_e32 v200, v123, v123
	v_lshlrev_b32_e32 v211, 16, v137
	v_mul_f32_e32 v124, v124, v198
	v_fma_f32 v124, -v218, v124, v211
	v_fmac_f32_e32 v200, v124, v124
	v_and_b32_e32 v211, 0xffff0000, v137
	v_mul_f32_e32 v125, v125, v198
	v_fma_f32 v125, -v218, v125, v211
	v_fmac_f32_e32 v200, v125, v125
	s_waitcnt vmcnt(27)
	v_lshlrev_b32_e32 v211, 16, v138
	v_mul_f32_e32 v98, v98, v198
	v_fma_f32 v98, -v218, v98, v211
	v_fmac_f32_e32 v200, v98, v98
	v_and_b32_e32 v211, 0xffff0000, v138
	v_mul_f32_e32 v99, v99, v198
	v_fma_f32 v99, -v218, v99, v211
	v_fmac_f32_e32 v200, v99, v99
	v_lshlrev_b32_e32 v211, 16, v139
	v_mul_f32_e32 v100, v100, v198
	v_fma_f32 v100, -v218, v100, v211
	v_fmac_f32_e32 v200, v100, v100
	v_and_b32_e32 v211, 0xffff0000, v139
	v_mul_f32_e32 v101, v101, v198
	v_fma_f32 v101, -v218, v101, v211
	v_fmac_f32_e32 v200, v101, v101
	s_waitcnt vmcnt(26)
	v_lshlrev_b32_e32 v211, 16, v140
	v_mul_f32_e32 v106, v106, v198
	v_fma_f32 v106, -v218, v106, v211
	v_fmac_f32_e32 v200, v106, v106
	v_and_b32_e32 v211, 0xffff0000, v140
	v_mul_f32_e32 v107, v107, v198
	v_fma_f32 v107, -v218, v107, v211
	v_fmac_f32_e32 v200, v107, v107
	v_lshlrev_b32_e32 v211, 16, v141
	v_mul_f32_e32 v108, v108, v198
	v_fma_f32 v108, -v218, v108, v211
	v_fmac_f32_e32 v200, v108, v108
	v_and_b32_e32 v211, 0xffff0000, v141
	v_mul_f32_e32 v109, v109, v198
	v_fma_f32 v109, -v218, v109, v211
	v_fmac_f32_e32 v200, v109, v109
	s_waitcnt vmcnt(25)
	v_lshlrev_b32_e32 v211, 16, v142
	v_mul_f32_e32 v82, v82, v198
	v_fma_f32 v82, -v218, v82, v211
	v_fmac_f32_e32 v200, v82, v82
	v_and_b32_e32 v211, 0xffff0000, v142
	v_mul_f32_e32 v83, v83, v198
	v_fma_f32 v83, -v218, v83, v211
	v_fmac_f32_e32 v200, v83, v83
	v_lshlrev_b32_e32 v211, 16, v143
	v_mul_f32_e32 v84, v84, v198
	v_fma_f32 v84, -v218, v84, v211
	v_fmac_f32_e32 v200, v84, v84
	v_and_b32_e32 v211, 0xffff0000, v143
	v_mul_f32_e32 v85, v85, v198
	v_fma_f32 v85, -v218, v85, v211
	v_fmac_f32_e32 v200, v85, v85
	s_waitcnt vmcnt(24)
	v_lshlrev_b32_e32 v211, 16, v144
	v_mul_f32_e32 v90, v90, v198
	v_fma_f32 v90, -v218, v90, v211
	v_fmac_f32_e32 v200, v90, v90
	v_and_b32_e32 v211, 0xffff0000, v144
	v_mul_f32_e32 v91, v91, v198
	v_fma_f32 v91, -v218, v91, v211
	v_fmac_f32_e32 v200, v91, v91
	v_lshlrev_b32_e32 v211, 16, v145
	v_mul_f32_e32 v92, v92, v198
	v_fma_f32 v92, -v218, v92, v211
	v_fmac_f32_e32 v200, v92, v92
	v_and_b32_e32 v211, 0xffff0000, v145
	v_mul_f32_e32 v93, v93, v198
	v_fma_f32 v93, -v218, v93, v211
	v_fmac_f32_e32 v200, v93, v93
	s_waitcnt vmcnt(23)
	v_lshlrev_b32_e32 v211, 16, v146
	v_mul_f32_e32 v66, v66, v198
	v_fma_f32 v66, -v218, v66, v211
	v_fmac_f32_e32 v200, v66, v66
	v_and_b32_e32 v211, 0xffff0000, v146
	v_mul_f32_e32 v67, v67, v198
	v_fma_f32 v67, -v218, v67, v211
	v_fmac_f32_e32 v200, v67, v67
	v_lshlrev_b32_e32 v211, 16, v147
	v_mul_f32_e32 v68, v68, v198
	v_fma_f32 v68, -v218, v68, v211
	v_fmac_f32_e32 v200, v68, v68
	v_and_b32_e32 v211, 0xffff0000, v147
	v_mul_f32_e32 v69, v69, v198
	v_fma_f32 v69, -v218, v69, v211
	v_fmac_f32_e32 v200, v69, v69
	s_waitcnt vmcnt(22)
	v_lshlrev_b32_e32 v211, 16, v148
	v_mul_f32_e32 v74, v74, v198
	v_fma_f32 v74, -v218, v74, v211
	v_fmac_f32_e32 v200, v74, v74
	v_and_b32_e32 v211, 0xffff0000, v148
	v_mul_f32_e32 v75, v75, v198
	v_fma_f32 v75, -v218, v75, v211
	v_fmac_f32_e32 v200, v75, v75
	v_lshlrev_b32_e32 v211, 16, v149
	v_mul_f32_e32 v76, v76, v198
	v_fma_f32 v76, -v218, v76, v211
	v_fmac_f32_e32 v200, v76, v76
	v_and_b32_e32 v211, 0xffff0000, v149
	v_mul_f32_e32 v77, v77, v198
	v_fma_f32 v77, -v218, v77, v211
	v_fmac_f32_e32 v200, v77, v77
	s_waitcnt vmcnt(21)
; __device__ __forceinline__ float bf2f(bf16_t b) { return __uint_as_float(((unsigned)b) << 16); }
; __device__ __forceinline__ int crow(int r, int hi) { return (r & 3) + 8 * (r >> 2) + 4 * hi; }
; __device__ __forceinline__ int crow(int r, int hi) { return (r & 3) + 8 * (r >> 2) + 4 * hi; }
; __device__ __forceinline__ void attn_body256(const bf16_t* __restrict__ Qb, const bf16_t* __restrict__ Kh, const bf16_t* __restrict__ Vh,
;                                              bf16_t* Ob, int seq, unsigned char* lds, float lam, int MODE, bf16_t* Ab, const float* wsub) {
;     ...
;     for (int r = 0; r < 16; ++r) { const int orow = crow(r, hi); float ss = 0.f;
; #pragma unroll
;       for (int d0 = 0; d0 < 8; ++d0) { const float v = bf2f(Ow[(long)orow * LDO + d0 * 32 + r32]) - lam * (o[d0][r] * rli[r]); o[d0][r] = v; ss += v * v; }
	v_lshlrev_b32_e32 v211, 16, v150
	v_mul_f32_e32 v50, v50, v198
	v_fma_f32 v50, -v218, v50, v211
	v_fmac_f32_e32 v200, v50, v50
	v_and_b32_e32 v211, 0xffff0000, v150
	v_mul_f32_e32 v51, v51, v198
	v_fma_f32 v51, -v218, v51, v211
	v_fmac_f32_e32 v200, v51, v51
	v_lshlrev_b32_e32 v211, 16, v151
	v_mul_f32_e32 v52, v52, v198
	v_fma_f32 v52, -v218, v52, v211
	v_fmac_f32_e32 v200, v52, v52
	v_and_b32_e32 v211, 0xffff0000, v151
	v_mul_f32_e32 v53, v53, v198
	v_fma_f32 v53, -v218, v53, v211
	v_fmac_f32_e32 v200, v53, v53
	s_waitcnt vmcnt(20)
	v_lshlrev_b32_e32 v211, 16, v152
	v_mul_f32_e32 v58, v58, v198
	v_fma_f32 v58, -v218, v58, v211
	v_fmac_f32_e32 v200, v58, v58
	v_and_b32_e32 v211, 0xffff0000, v152
	v_mul_f32_e32 v59, v59, v198
	v_fma_f32 v59, -v218, v59, v211
	v_fmac_f32_e32 v200, v59, v59
	v_lshlrev_b32_e32 v211, 16, v153
	v_mul_f32_e32 v60, v60, v198
	v_fma_f32 v60, -v218, v60, v211
	v_fmac_f32_e32 v200, v60, v60
	v_and_b32_e32 v211, 0xffff0000, v153
	v_mul_f32_e32 v61, v61, v198
	v_fma_f32 v61, -v218, v61, v211
	v_fmac_f32_e32 v200, v61, v61
	s_waitcnt vmcnt(19)
	v_lshlrev_b32_e32 v211, 16, v154
	v_mul_f32_e32 v34, v34, v198
	v_fma_f32 v34, -v218, v34, v211
	v_fmac_f32_e32 v200, v34, v34
	v_and_b32_e32 v211, 0xffff0000, v154
	v_mul_f32_e32 v35, v35, v198
	v_fma_f32 v35, -v218, v35, v211
	v_fmac_f32_e32 v200, v35, v35
	v_lshlrev_b32_e32 v211, 16, v155
	v_mul_f32_e32 v36, v36, v198
	v_fma_f32 v36, -v218, v36, v211
	v_fmac_f32_e32 v200, v36, v36
	v_and_b32_e32 v211, 0xffff0000, v155
	v_mul_f32_e32 v37, v37, v198
	v_fma_f32 v37, -v218, v37, v211
	v_fmac_f32_e32 v200, v37, v37
	s_waitcnt vmcnt(18)
	v_lshlrev_b32_e32 v211, 16, v156
	v_mul_f32_e32 v42, v42, v198
	v_fma_f32 v42, -v218, v42, v211
	v_fmac_f32_e32 v200, v42, v42
	v_and_b32_e32 v211, 0xffff0000, v156
	v_mul_f32_e32 v43, v43, v198
	v_fma_f32 v43, -v218, v43, v211
	v_fmac_f32_e32 v200, v43, v43
	v_lshlrev_b32_e32 v211, 16, v157
	v_mul_f32_e32 v44, v44, v198
	v_fma_f32 v44, -v218, v44, v211
	v_fmac_f32_e32 v200, v44, v44
	v_and_b32_e32 v211, 0xffff0000, v157
	v_mul_f32_e32 v45, v45, v198
	v_fma_f32 v45, -v218, v45, v211
	v_fmac_f32_e32 v200, v45, v45
	s_waitcnt vmcnt(17)
	v_lshlrev_b32_e32 v211, 16, v158
	v_mul_f32_e32 v18, v18, v198
	v_fma_f32 v18, -v218, v18, v211
	v_fmac_f32_e32 v200, v18, v18
	v_and_b32_e32 v211, 0xffff0000, v158
	v_mul_f32_e32 v19, v19, v198
	v_fma_f32 v19, -v218, v19, v211
	v_fmac_f32_e32 v200, v19, v19
	v_lshlrev_b32_e32 v211, 16, v159
	v_mul_f32_e32 v20, v20, v198
	v_fma_f32 v20, -v218, v20, v211
	v_fmac_f32_e32 v200, v20, v20
	v_and_b32_e32 v211, 0xffff0000, v159
	v_mul_f32_e32 v21, v21, v198
	v_fma_f32 v21, -v218, v21, v211
	v_fmac_f32_e32 v200, v21, v21
	s_waitcnt vmcnt(16)
	v_lshlrev_b32_e32 v211, 16, v160
	v_mul_f32_e32 v26, v26, v198
	v_fma_f32 v26, -v218, v26, v211
	v_fmac_f32_e32 v200, v26, v26
	v_and_b32_e32 v211, 0xffff0000, v160
	v_mul_f32_e32 v27, v27, v198
	v_fma_f32 v27, -v218, v27, v211
	v_fmac_f32_e32 v200, v27, v27
	v_lshlrev_b32_e32 v211, 16, v161
	v_mul_f32_e32 v28, v28, v198
	v_fma_f32 v28, -v218, v28, v211
	v_fmac_f32_e32 v200, v28, v28
	v_and_b32_e32 v211, 0xffff0000, v161
	v_mul_f32_e32 v29, v29, v198
	v_fma_f32 v29, -v218, v29, v211
	v_fmac_f32_e32 v200, v29, v29
	s_waitcnt vmcnt(15)
	v_lshlrev_b32_e32 v211, 16, v162
	v_mul_f32_e32 v6, v6, v199
	v_fma_f32 v6, -v218, v6, v211
	v_fmac_f32_e32 v201, v6, v6
	v_and_b32_e32 v211, 0xffff0000, v162
	v_mul_f32_e32 v7, v7, v199
	v_fma_f32 v7, -v218, v7, v211
	v_fmac_f32_e32 v201, v7, v7
	v_lshlrev_b32_e32 v211, 16, v163
	v_mul_f32_e32 v8, v8, v199
	v_fma_f32 v8, -v218, v8, v211
	v_fmac_f32_e32 v201, v8, v8
	v_and_b32_e32 v211, 0xffff0000, v163
	v_mul_f32_e32 v9, v9, v199
	v_fma_f32 v9, -v218, v9, v211
	v_fmac_f32_e32 v201, v9, v9
	s_waitcnt vmcnt(14)
	v_lshlrev_b32_e32 v211, 16, v164
	v_mul_f32_e32 v14, v14, v199
	v_fma_f32 v14, -v218, v14, v211
	v_fmac_f32_e32 v201, v14, v14
	v_and_b32_e32 v211, 0xffff0000, v164
	v_mul_f32_e32 v15, v15, v199
	v_fma_f32 v15, -v218, v15, v211
	v_fmac_f32_e32 v201, v15, v15
	v_lshlrev_b32_e32 v211, 16, v165
	v_mul_f32_e32 v16, v16, v199
	v_fma_f32 v16, -v218, v16, v211
	v_fmac_f32_e32 v201, v16, v16
	v_and_b32_e32 v211, 0xffff0000, v165
	v_mul_f32_e32 v17, v17, v199
	v_fma_f32 v17, -v218, v17, v211
	v_fmac_f32_e32 v201, v17, v17
	s_waitcnt vmcnt(13)
	v_lshlrev_b32_e32 v211, 16, v166
	v_mul_f32_e32 v118, v118, v199
	v_fma_f32 v118, -v218, v118, v211
	v_fmac_f32_e32 v201, v118, v118
	v_and_b32_e32 v211, 0xffff0000, v166
	v_mul_f32_e32 v119, v119, v199
	v_fma_f32 v119, -v218, v119, v211
	v_fmac_f32_e32 v201, v119, v119
	v_lshlrev_b32_e32 v211, 16, v167
	v_mul_f32_e32 v120, v120, v199
	v_fma_f32 v120, -v218, v120, v211
	v_fmac_f32_e32 v201, v120, v120
	v_and_b32_e32 v211, 0xffff0000, v167
	v_mul_f32_e32 v121, v121, v199
	v_fma_f32 v121, -v218, v121, v211
	v_fmac_f32_e32 v201, v121, v121
	s_waitcnt vmcnt(12)
	v_lshlrev_b32_e32 v211, 16, v168
	v_mul_f32_e32 v126, v126, v199
	v_fma_f32 v126, -v218, v126, v211
	v_fmac_f32_e32 v201, v126, v126
	v_and_b32_e32 v211, 0xffff0000, v168
	v_mul_f32_e32 v127, v127, v199
	v_fma_f32 v127, -v218, v127, v211
	v_fmac_f32_e32 v201, v127, v127
	v_lshlrev_b32_e32 v211, 16, v169
	v_mul_f32_e32 v128, v128, v199
	v_fma_f32 v128, -v218, v128, v211
	v_fmac_f32_e32 v201, v128, v128
	v_and_b32_e32 v211, 0xffff0000, v169
	v_mul_f32_e32 v129, v129, v199
	v_fma_f32 v129, -v218, v129, v211
	v_fmac_f32_e32 v201, v129, v129
	s_waitcnt vmcnt(11)
; __device__ __forceinline__ float bf2f(bf16_t b) { return __uint_as_float(((unsigned)b) << 16); }
; __device__ __forceinline__ int crow(int r, int hi) { return (r & 3) + 8 * (r >> 2) + 4 * hi; }
; __device__ __forceinline__ int crow(int r, int hi) { return (r & 3) + 8 * (r >> 2) + 4 * hi; }
; __device__ __forceinline__ void attn_body256(const bf16_t* __restrict__ Qb, const bf16_t* __restrict__ Kh, const bf16_t* __restrict__ Vh,
;                                              bf16_t* Ob, int seq, unsigned char* lds, float lam, int MODE, bf16_t* Ab, const float* wsub) {
;     ...
;     for (int r = 0; r < 16; ++r) { const int orow = crow(r, hi); float ss = 0.f;
; #pragma unroll
;       for (int d0 = 0; d0 < 8; ++d0) { const float v = bf2f(Ow[(long)orow * LDO + d0 * 32 + r32]) - lam * (o[d0][r] * rli[r]); o[d0][r] = v; ss += v * v; }
	v_lshlrev_b32_e32 v211, 16, v170
	v_mul_f32_e32 v102, v102, v199
	v_fma_f32 v102, -v218, v102, v211
	v_fmac_f32_e32 v201, v102, v102
	v_and_b32_e32 v211, 0xffff0000, v170
	v_mul_f32_e32 v103, v103, v199
	v_fma_f32 v103, -v218, v103, v211
	v_fmac_f32_e32 v201, v103, v103
	v_lshlrev_b32_e32 v211, 16, v171
	v_mul_f32_e32 v104, v104, v199
	v_fma_f32 v104, -v218, v104, v211
	v_fmac_f32_e32 v201, v104, v104
	v_and_b32_e32 v211, 0xffff0000, v171
	v_mul_f32_e32 v105, v105, v199
	v_fma_f32 v105, -v218, v105, v211
	v_fmac_f32_e32 v201, v105, v105
	s_waitcnt vmcnt(10)
	v_lshlrev_b32_e32 v211, 16, v172
	v_mul_f32_e32 v110, v110, v199
	v_fma_f32 v110, -v218, v110, v211
	v_fmac_f32_e32 v201, v110, v110
	v_and_b32_e32 v211, 0xffff0000, v172
	v_mul_f32_e32 v111, v111, v199
	v_fma_f32 v111, -v218, v111, v211
	v_fmac_f32_e32 v201, v111, v111
	v_lshlrev_b32_e32 v211, 16, v173
	v_mul_f32_e32 v112, v112, v199
	v_fma_f32 v112, -v218, v112, v211
	v_fmac_f32_e32 v201, v112, v112
	v_and_b32_e32 v211, 0xffff0000, v173
	v_mul_f32_e32 v113, v113, v199
	v_fma_f32 v113, -v218, v113, v211
	v_fmac_f32_e32 v201, v113, v113
	s_waitcnt vmcnt(9)
	v_lshlrev_b32_e32 v211, 16, v174
	v_mul_f32_e32 v86, v86, v199
	v_fma_f32 v86, -v218, v86, v211
	v_fmac_f32_e32 v201, v86, v86
	v_and_b32_e32 v211, 0xffff0000, v174
	v_mul_f32_e32 v87, v87, v199
	v_fma_f32 v87, -v218, v87, v211
	v_fmac_f32_e32 v201, v87, v87
	v_lshlrev_b32_e32 v211, 16, v175
	v_mul_f32_e32 v88, v88, v199
	v_fma_f32 v88, -v218, v88, v211
	v_fmac_f32_e32 v201, v88, v88
	v_and_b32_e32 v211, 0xffff0000, v175
	v_mul_f32_e32 v89, v89, v199
	v_fma_f32 v89, -v218, v89, v211
	v_fmac_f32_e32 v201, v89, v89
	s_waitcnt vmcnt(8)
	v_lshlrev_b32_e32 v211, 16, v176
	v_mul_f32_e32 v94, v94, v199
	v_fma_f32 v94, -v218, v94, v211
	v_fmac_f32_e32 v201, v94, v94
	v_and_b32_e32 v211, 0xffff0000, v176
	v_mul_f32_e32 v95, v95, v199
	v_fma_f32 v95, -v218, v95, v211
	v_fmac_f32_e32 v201, v95, v95
	v_lshlrev_b32_e32 v211, 16, v177
	v_mul_f32_e32 v96, v96, v199
	v_fma_f32 v96, -v218, v96, v211
	v_fmac_f32_e32 v201, v96, v96
	v_and_b32_e32 v211, 0xffff0000, v177
	v_mul_f32_e32 v97, v97, v199
	v_fma_f32 v97, -v218, v97, v211
	v_fmac_f32_e32 v201, v97, v97
	s_waitcnt vmcnt(7)
	v_lshlrev_b32_e32 v211, 16, v178
	v_mul_f32_e32 v70, v70, v199
	v_fma_f32 v70, -v218, v70, v211
	v_fmac_f32_e32 v201, v70, v70
	v_and_b32_e32 v211, 0xffff0000, v178
	v_mul_f32_e32 v71, v71, v199
	v_fma_f32 v71, -v218, v71, v211
	v_fmac_f32_e32 v201, v71, v71
	v_lshlrev_b32_e32 v211, 16, v179
	v_mul_f32_e32 v72, v72, v199
	v_fma_f32 v72, -v218, v72, v211
	v_fmac_f32_e32 v201, v72, v72
	v_and_b32_e32 v211, 0xffff0000, v179
	v_mul_f32_e32 v73, v73, v199
	v_fma_f32 v73, -v218, v73, v211
	v_fmac_f32_e32 v201, v73, v73
	s_waitcnt vmcnt(6)
	v_lshlrev_b32_e32 v211, 16, v180
	v_mul_f32_e32 v78, v78, v199
	v_fma_f32 v78, -v218, v78, v211
	v_fmac_f32_e32 v201, v78, v78
	v_and_b32_e32 v211, 0xffff0000, v180
	v_mul_f32_e32 v79, v79, v199
	v_fma_f32 v79, -v218, v79, v211
	v_fmac_f32_e32 v201, v79, v79
	v_lshlrev_b32_e32 v211, 16, v181
	v_mul_f32_e32 v80, v80, v199
	v_fma_f32 v80, -v218, v80, v211
	v_fmac_f32_e32 v201, v80, v80
	v_and_b32_e32 v211, 0xffff0000, v181
	v_mul_f32_e32 v81, v81, v199
	v_fma_f32 v81, -v218, v81, v211
	v_fmac_f32_e32 v201, v81, v81
	s_waitcnt vmcnt(5)
	v_lshlrev_b32_e32 v211, 16, v182
	v_mul_f32_e32 v54, v54, v199
	v_fma_f32 v54, -v218, v54, v211
	v_fmac_f32_e32 v201, v54, v54
	v_and_b32_e32 v211, 0xffff0000, v182
	v_mul_f32_e32 v55, v55, v199
	v_fma_f32 v55, -v218, v55, v211
	v_fmac_f32_e32 v201, v55, v55
	v_lshlrev_b32_e32 v211, 16, v183
	v_mul_f32_e32 v56, v56, v199
	v_fma_f32 v56, -v218, v56, v211
	v_fmac_f32_e32 v201, v56, v56
	v_and_b32_e32 v211, 0xffff0000, v183
	v_mul_f32_e32 v57, v57, v199
	v_fma_f32 v57, -v218, v57, v211
	v_fmac_f32_e32 v201, v57, v57
	s_waitcnt vmcnt(4)
	v_lshlrev_b32_e32 v211, 16, v184
	v_mul_f32_e32 v62, v62, v199
	v_fma_f32 v62, -v218, v62, v211
	v_fmac_f32_e32 v201, v62, v62
	v_and_b32_e32 v211, 0xffff0000, v184
	v_mul_f32_e32 v63, v63, v199
	v_fma_f32 v63, -v218, v63, v211
	v_fmac_f32_e32 v201, v63, v63
	v_lshlrev_b32_e32 v211, 16, v185
	v_mul_f32_e32 v64, v64, v199
	v_fma_f32 v64, -v218, v64, v211
	v_fmac_f32_e32 v201, v64, v64
	v_and_b32_e32 v211, 0xffff0000, v185
	v_mul_f32_e32 v65, v65, v199
	v_fma_f32 v65, -v218, v65, v211
	v_fmac_f32_e32 v201, v65, v65
	s_waitcnt vmcnt(3)
	v_lshlrev_b32_e32 v211, 16, v186
	v_mul_f32_e32 v38, v38, v199
	v_fma_f32 v38, -v218, v38, v211
	v_fmac_f32_e32 v201, v38, v38
	v_and_b32_e32 v211, 0xffff0000, v186
	v_mul_f32_e32 v39, v39, v199
	v_fma_f32 v39, -v218, v39, v211
	v_fmac_f32_e32 v201, v39, v39
	v_lshlrev_b32_e32 v211, 16, v187
	v_mul_f32_e32 v40, v40, v199
	v_fma_f32 v40, -v218, v40, v211
	v_fmac_f32_e32 v201, v40, v40
	v_and_b32_e32 v211, 0xffff0000, v187
	v_mul_f32_e32 v41, v41, v199
	v_fma_f32 v41, -v218, v41, v211
	v_fmac_f32_e32 v201, v41, v41
	s_waitcnt vmcnt(2)
	v_lshlrev_b32_e32 v211, 16, v188
	v_mul_f32_e32 v46, v46, v199
	v_fma_f32 v46, -v218, v46, v211
	v_fmac_f32_e32 v201, v46, v46
	v_and_b32_e32 v211, 0xffff0000, v188
	v_mul_f32_e32 v47, v47, v199
	v_fma_f32 v47, -v218, v47, v211
	v_fmac_f32_e32 v201, v47, v47
	v_lshlrev_b32_e32 v211, 16, v189
	v_mul_f32_e32 v48, v48, v199
	v_fma_f32 v48, -v218, v48, v211
	v_fmac_f32_e32 v201, v48, v48
	v_and_b32_e32 v211, 0xffff0000, v189
	v_mul_f32_e32 v49, v49, v199
	v_fma_f32 v49, -v218, v49, v211
	v_fmac_f32_e32 v201, v49, v49
	s_waitcnt vmcnt(1)
; __device__ __forceinline__ bf16_t f2bf(float x) { return (bf16_t)(cvt_pk_bf16(x, x) & 0xffffu); }
; __device__ __forceinline__ float bf2f(bf16_t b) { return __uint_as_float(((unsigned)b) << 16); }
; __device__ __forceinline__ int crow(int r, int hi) { return (r & 3) + 8 * (r >> 2) + 4 * hi; }
; __device__ __forceinline__ int crow(int r, int hi) { return (r & 3) + 8 * (r >> 2) + 4 * hi; }
; __device__ __forceinline__ void attn_body256(const bf16_t* __restrict__ Qb, const bf16_t* __restrict__ Kh, const bf16_t* __restrict__ Vh,
;                                              bf16_t* Ob, int seq, unsigned char* lds, float lam, int MODE, bf16_t* Ab, const float* wsub) {
;     ...
;     for (int r = 0; r < 16; ++r) { const int orow = crow(r, hi); float ss = 0.f;
; #pragma unroll
;       for (int d0 = 0; d0 < 8; ++d0) { const float v = bf2f(Ow[(long)orow * LDO + d0 * 32 + r32]) - lam * (o[d0][r] * rli[r]); o[d0][r] = v; ss += v * v; }
;       ss += __shfl_xor(ss, 1, 64); ss += __shfl_xor(ss, 2, 64); ss += __shfl_xor(ss, 4, 64); ss += __shfl_xor(ss, 8, 64); ss += __shfl_xor(ss, 16, 64);
;       const float rstd = rsqrtf(ss * (1.f / 256.f) + NORM_EPS);
; #pragma unroll
;       for (int d0 = 0; d0 < 8; ++d0) Aw[(long)orow * LDO + d0 * 32 + r32] = f2bf(o[d0][r] * rstd * wv[d0]); }
	v_lshlrev_b32_e32 v211, 16, v190
	v_mul_f32_e32 v22, v22, v199
	v_fma_f32 v22, -v218, v22, v211
	v_fmac_f32_e32 v201, v22, v22
	v_and_b32_e32 v211, 0xffff0000, v190
	v_mul_f32_e32 v23, v23, v199
	v_fma_f32 v23, -v218, v23, v211
	v_fmac_f32_e32 v201, v23, v23
	v_lshlrev_b32_e32 v211, 16, v191
	v_mul_f32_e32 v24, v24, v199
	v_fma_f32 v24, -v218, v24, v211
	v_fmac_f32_e32 v201, v24, v24
	v_and_b32_e32 v211, 0xffff0000, v191
	v_mul_f32_e32 v25, v25, v199
	v_fma_f32 v25, -v218, v25, v211
	v_fmac_f32_e32 v201, v25, v25
	s_waitcnt vmcnt(0)
	v_lshlrev_b32_e32 v211, 16, v192
	v_mul_f32_e32 v30, v30, v199
	v_fma_f32 v30, -v218, v30, v211
	v_fmac_f32_e32 v201, v30, v30
	v_and_b32_e32 v211, 0xffff0000, v192
	v_mul_f32_e32 v31, v31, v199
	v_fma_f32 v31, -v218, v31, v211
	v_fmac_f32_e32 v201, v31, v31
	v_lshlrev_b32_e32 v211, 16, v193
	v_mul_f32_e32 v32, v32, v199
	v_fma_f32 v32, -v218, v32, v211
	v_fmac_f32_e32 v201, v32, v32
	v_and_b32_e32 v211, 0xffff0000, v193
	v_mul_f32_e32 v33, v33, v199
	v_fma_f32 v33, -v218, v33, v211
	v_fmac_f32_e32 v201, v33, v33
	v_mov_b32_e32 v212, v200
	v_mov_b32_e32 v213, v201
	s_nop 1
	v_permlane32_swap_b32_e32 v200, v212
	v_permlane32_swap_b32_e32 v201, v213
	v_add_f32_e32 v200, v200, v212
	v_add_f32_e32 v201, v201, v213
	v_mov_b32_e32 v212, v200
	v_mov_b32_e32 v213, v201
	s_nop 1
	v_permlane16_swap_b32_e32 v200, v212
	v_permlane16_swap_b32_e32 v201, v213
	v_add_f32_e32 v200, v200, v212
	v_add_f32_e32 v201, v201, v213
	v_mul_f32_e32 v200, 0x3b800000, v200
	v_add_f32_e32 v200, 0x3727c5ac, v200
	v_mul_f32_e32 v201, 0x3b800000, v201
	v_add_f32_e32 v201, 0x3727c5ac, v201
	v_rsq_f32_e32 v200, v200
	v_rsq_f32_e32 v201, v201
	s_nop 0
	v_mul_f32_e32 v200, 0x3f24fd5c, v200
	v_mul_f32_e32 v201, 0x3f24fd5c, v201
	global_load_dwordx4 v[130:133], v210, s[28:29]
	global_load_dwordx4 v[134:137], v210, s[28:29] offset:64
	global_load_dwordx4 v[138:141], v210, s[28:29] offset:128
	global_load_dwordx4 v[142:145], v210, s[28:29] offset:192
	s_waitcnt vmcnt(3)
	v_mul_f32_e32 v2, v2, v200
	v_mul_f32_e32 v2, v2, v130
	v_mul_f32_e32 v3, v3, v200
	v_mul_f32_e32 v3, v3, v131
	v_mul_f32_e32 v4, v4, v200
	v_mul_f32_e32 v4, v4, v132
	v_mul_f32_e32 v5, v5, v200
	v_mul_f32_e32 v5, v5, v133
	v_cvt_pk_bf16_f32 v2, v2, v3
	v_cvt_pk_bf16_f32 v3, v4, v5
	global_store_dwordx2 v[204:205], v[2:3], off
	v_mul_f32_e32 v6, v6, v201
	v_mul_f32_e32 v6, v6, v130
	v_mul_f32_e32 v7, v7, v201
	v_mul_f32_e32 v7, v7, v131
	v_mul_f32_e32 v8, v8, v201
	v_mul_f32_e32 v8, v8, v132
	v_mul_f32_e32 v9, v9, v201
	v_mul_f32_e32 v9, v9, v133
	v_cvt_pk_bf16_f32 v6, v6, v7
	v_cvt_pk_bf16_f32 v7, v8, v9
	global_store_dwordx2 v[206:207], v[6:7], off
	s_waitcnt vmcnt(2)
	v_mul_f32_e32 v10, v10, v200
	v_mul_f32_e32 v10, v10, v134
	v_mul_f32_e32 v11, v11, v200
	v_mul_f32_e32 v11, v11, v135
	v_mul_f32_e32 v12, v12, v200
	v_mul_f32_e32 v12, v12, v136
	v_mul_f32_e32 v13, v13, v200
	v_mul_f32_e32 v13, v13, v137
	v_cvt_pk_bf16_f32 v10, v10, v11
	v_cvt_pk_bf16_f32 v11, v12, v13
	global_store_dwordx2 v[204:205], v[10:11], off offset:32
	v_mul_f32_e32 v14, v14, v201
	v_mul_f32_e32 v14, v14, v134
	v_mul_f32_e32 v15, v15, v201
	v_mul_f32_e32 v15, v15, v135
	v_mul_f32_e32 v16, v16, v201
	v_mul_f32_e32 v16, v16, v136
	v_mul_f32_e32 v17, v17, v201
	v_mul_f32_e32 v17, v17, v137
	v_cvt_pk_bf16_f32 v14, v14, v15
	v_cvt_pk_bf16_f32 v15, v16, v17
	global_store_dwordx2 v[206:207], v[14:15], off offset:32
	s_waitcnt vmcnt(1)
	v_mul_f32_e32 v114, v114, v200
	v_mul_f32_e32 v114, v114, v138
	v_mul_f32_e32 v115, v115, v200
	v_mul_f32_e32 v115, v115, v139
	v_mul_f32_e32 v116, v116, v200
	v_mul_f32_e32 v116, v116, v140
	v_mul_f32_e32 v117, v117, v200
	v_mul_f32_e32 v117, v117, v141
	v_cvt_pk_bf16_f32 v114, v114, v115
	v_cvt_pk_bf16_f32 v115, v116, v117
	global_store_dwordx2 v[204:205], v[114:115], off offset:64
	v_mul_f32_e32 v118, v118, v201
	v_mul_f32_e32 v118, v118, v138
	v_mul_f32_e32 v119, v119, v201
	v_mul_f32_e32 v119, v119, v139
	v_mul_f32_e32 v120, v120, v201
	v_mul_f32_e32 v120, v120, v140
	v_mul_f32_e32 v121, v121, v201
	v_mul_f32_e32 v121, v121, v141
	v_cvt_pk_bf16_f32 v118, v118, v119
	v_cvt_pk_bf16_f32 v119, v120, v121
	global_store_dwordx2 v[206:207], v[118:119], off offset:64
	s_waitcnt vmcnt(0)
	v_mul_f32_e32 v122, v122, v200
	v_mul_f32_e32 v122, v122, v142
	v_mul_f32_e32 v123, v123, v200
	v_mul_f32_e32 v123, v123, v143
	v_mul_f32_e32 v124, v124, v200
	v_mul_f32_e32 v124, v124, v144
	v_mul_f32_e32 v125, v125, v200
	v_mul_f32_e32 v125, v125, v145
	v_cvt_pk_bf16_f32 v122, v122, v123
	v_cvt_pk_bf16_f32 v123, v124, v125
	global_store_dwordx2 v[204:205], v[122:123], off offset:96
	v_mul_f32_e32 v126, v126, v201
	v_mul_f32_e32 v126, v126, v142
	v_mul_f32_e32 v127, v127, v201
	v_mul_f32_e32 v127, v127, v143
	v_mul_f32_e32 v128, v128, v201
	v_mul_f32_e32 v128, v128, v144
	v_mul_f32_e32 v129, v129, v201
	v_mul_f32_e32 v129, v129, v145
	v_cvt_pk_bf16_f32 v126, v126, v127
	v_cvt_pk_bf16_f32 v127, v128, v129
	global_store_dwordx2 v[206:207], v[126:127], off offset:96
	global_load_dwordx4 v[130:133], v210, s[28:29] offset:256
	global_load_dwordx4 v[134:137], v210, s[28:29] offset:320
	global_load_dwordx4 v[138:141], v210, s[28:29] offset:384
	global_load_dwordx4 v[142:145], v210, s[28:29] offset:448
	s_waitcnt vmcnt(3)
; __device__ __forceinline__ bf16_t f2bf(float x) { return (bf16_t)(cvt_pk_bf16(x, x) & 0xffffu); }
; __device__ __forceinline__ float bf2f(bf16_t b) { return __uint_as_float(((unsigned)b) << 16); }
; __device__ __forceinline__ int crow(int r, int hi) { return (r & 3) + 8 * (r >> 2) + 4 * hi; }
; __device__ __forceinline__ int crow(int r, int hi) { return (r & 3) + 8 * (r >> 2) + 4 * hi; }
; __device__ __forceinline__ void attn_body256(const bf16_t* __restrict__ Qb, const bf16_t* __restrict__ Kh, const bf16_t* __restrict__ Vh,
;                                              bf16_t* Ob, int seq, unsigned char* lds, float lam, int MODE, bf16_t* Ab, const float* wsub) {
;     ...
;     for (int d0 = 0; d0 < 8; ++d0) wv[d0] = wsub[d0 * 32 + r32] * (1.f - LAMBDA_INIT);
; #pragma unroll
;     for (int r = 0; r < 16; ++r) { const int orow = crow(r, hi); float ss = 0.f;
; #pragma unroll
;       for (int d0 = 0; d0 < 8; ++d0) { const float v = bf2f(Ow[(long)orow * LDO + d0 * 32 + r32]) - lam * (o[d0][r] * rli[r]); o[d0][r] = v; ss += v * v; }
;       ss += __shfl_xor(ss, 1, 64); ss += __shfl_xor(ss, 2, 64); ss += __shfl_xor(ss, 4, 64); ss += __shfl_xor(ss, 8, 64); ss += __shfl_xor(ss, 16, 64);
;       const float rstd = rsqrtf(ss * (1.f / 256.f) + NORM_EPS);
; #pragma unroll
;       for (int d0 = 0; d0 < 8; ++d0) Aw[(long)orow * LDO + d0 * 32 + r32] = f2bf(o[d0][r] * rstd * wv[d0]); }
	v_mul_f32_e32 v98, v98, v200
	v_mul_f32_e32 v98, v98, v130
	v_mul_f32_e32 v99, v99, v200
	v_mul_f32_e32 v99, v99, v131
	v_mul_f32_e32 v100, v100, v200
	v_mul_f32_e32 v100, v100, v132
	v_mul_f32_e32 v101, v101, v200
	v_mul_f32_e32 v101, v101, v133
	v_cvt_pk_bf16_f32 v98, v98, v99
	v_cvt_pk_bf16_f32 v99, v100, v101
	global_store_dwordx2 v[204:205], v[98:99], off offset:128
	v_mul_f32_e32 v102, v102, v201
	v_mul_f32_e32 v102, v102, v130
	v_mul_f32_e32 v103, v103, v201
	v_mul_f32_e32 v103, v103, v131
	v_mul_f32_e32 v104, v104, v201
	v_mul_f32_e32 v104, v104, v132
	v_mul_f32_e32 v105, v105, v201
	v_mul_f32_e32 v105, v105, v133
	v_cvt_pk_bf16_f32 v102, v102, v103
	v_cvt_pk_bf16_f32 v103, v104, v105
	global_store_dwordx2 v[206:207], v[102:103], off offset:128
	s_waitcnt vmcnt(2)
	v_mul_f32_e32 v106, v106, v200
	v_mul_f32_e32 v106, v106, v134
	v_mul_f32_e32 v107, v107, v200
	v_mul_f32_e32 v107, v107, v135
	v_mul_f32_e32 v108, v108, v200
	v_mul_f32_e32 v108, v108, v136
	v_mul_f32_e32 v109, v109, v200
	v_mul_f32_e32 v109, v109, v137
	v_cvt_pk_bf16_f32 v106, v106, v107
	v_cvt_pk_bf16_f32 v107, v108, v109
	global_store_dwordx2 v[204:205], v[106:107], off offset:160
	v_mul_f32_e32 v110, v110, v201
	v_mul_f32_e32 v110, v110, v134
	v_mul_f32_e32 v111, v111, v201
	v_mul_f32_e32 v111, v111, v135
	v_mul_f32_e32 v112, v112, v201
	v_mul_f32_e32 v112, v112, v136
	v_mul_f32_e32 v113, v113, v201
	v_mul_f32_e32 v113, v113, v137
	v_cvt_pk_bf16_f32 v110, v110, v111
	v_cvt_pk_bf16_f32 v111, v112, v113
	global_store_dwordx2 v[206:207], v[110:111], off offset:160
	s_waitcnt vmcnt(1)
	v_mul_f32_e32 v82, v82, v200
	v_mul_f32_e32 v82, v82, v138
	v_mul_f32_e32 v83, v83, v200
	v_mul_f32_e32 v83, v83, v139
	v_mul_f32_e32 v84, v84, v200
	v_mul_f32_e32 v84, v84, v140
	v_mul_f32_e32 v85, v85, v200
	v_mul_f32_e32 v85, v85, v141
	v_cvt_pk_bf16_f32 v82, v82, v83
	v_cvt_pk_bf16_f32 v83, v84, v85
	global_store_dwordx2 v[204:205], v[82:83], off offset:192
	v_mul_f32_e32 v86, v86, v201
	v_mul_f32_e32 v86, v86, v138
	v_mul_f32_e32 v87, v87, v201
	v_mul_f32_e32 v87, v87, v139
	v_mul_f32_e32 v88, v88, v201
	v_mul_f32_e32 v88, v88, v140
	v_mul_f32_e32 v89, v89, v201
	v_mul_f32_e32 v89, v89, v141
	v_cvt_pk_bf16_f32 v86, v86, v87
	v_cvt_pk_bf16_f32 v87, v88, v89
	global_store_dwordx2 v[206:207], v[86:87], off offset:192
	s_waitcnt vmcnt(0)
	v_mul_f32_e32 v90, v90, v200
	v_mul_f32_e32 v90, v90, v142
	v_mul_f32_e32 v91, v91, v200
	v_mul_f32_e32 v91, v91, v143
	v_mul_f32_e32 v92, v92, v200
	v_mul_f32_e32 v92, v92, v144
	v_mul_f32_e32 v93, v93, v200
	v_mul_f32_e32 v93, v93, v145
	v_cvt_pk_bf16_f32 v90, v90, v91
	v_cvt_pk_bf16_f32 v91, v92, v93
	global_store_dwordx2 v[204:205], v[90:91], off offset:224
	v_mul_f32_e32 v94, v94, v201
	v_mul_f32_e32 v94, v94, v142
	v_mul_f32_e32 v95, v95, v201
	v_mul_f32_e32 v95, v95, v143
	v_mul_f32_e32 v96, v96, v201
	v_mul_f32_e32 v96, v96, v144
	v_mul_f32_e32 v97, v97, v201
	v_mul_f32_e32 v97, v97, v145
	v_cvt_pk_bf16_f32 v94, v94, v95
	v_cvt_pk_bf16_f32 v95, v96, v97
	global_store_dwordx2 v[206:207], v[94:95], off offset:224
	global_load_dwordx4 v[130:133], v210, s[28:29] offset:512
	global_load_dwordx4 v[134:137], v210, s[28:29] offset:576
	global_load_dwordx4 v[138:141], v210, s[28:29] offset:640
	global_load_dwordx4 v[142:145], v210, s[28:29] offset:704
	s_waitcnt vmcnt(3)
	v_mul_f32_e32 v66, v66, v200
	v_mul_f32_e32 v66, v66, v130
	v_mul_f32_e32 v67, v67, v200
	v_mul_f32_e32 v67, v67, v131
	v_mul_f32_e32 v68, v68, v200
	v_mul_f32_e32 v68, v68, v132
	v_mul_f32_e32 v69, v69, v200
	v_mul_f32_e32 v69, v69, v133
	v_cvt_pk_bf16_f32 v66, v66, v67
	v_cvt_pk_bf16_f32 v67, v68, v69
	global_store_dwordx2 v[204:205], v[66:67], off offset:256
	v_mul_f32_e32 v70, v70, v201
	v_mul_f32_e32 v70, v70, v130
	v_mul_f32_e32 v71, v71, v201
	v_mul_f32_e32 v71, v71, v131
	v_mul_f32_e32 v72, v72, v201
	v_mul_f32_e32 v72, v72, v132
	v_mul_f32_e32 v73, v73, v201
	v_mul_f32_e32 v73, v73, v133
	v_cvt_pk_bf16_f32 v70, v70, v71
	v_cvt_pk_bf16_f32 v71, v72, v73
	global_store_dwordx2 v[206:207], v[70:71], off offset:256
	s_waitcnt vmcnt(2)
	v_mul_f32_e32 v74, v74, v200
	v_mul_f32_e32 v74, v74, v134
	v_mul_f32_e32 v75, v75, v200
	v_mul_f32_e32 v75, v75, v135
	v_mul_f32_e32 v76, v76, v200
	v_mul_f32_e32 v76, v76, v136
	v_mul_f32_e32 v77, v77, v200
	v_mul_f32_e32 v77, v77, v137
	v_cvt_pk_bf16_f32 v74, v74, v75
	v_cvt_pk_bf16_f32 v75, v76, v77
	global_store_dwordx2 v[204:205], v[74:75], off offset:288
	v_mul_f32_e32 v78, v78, v201
	v_mul_f32_e32 v78, v78, v134
	v_mul_f32_e32 v79, v79, v201
	v_mul_f32_e32 v79, v79, v135
	v_mul_f32_e32 v80, v80, v201
	v_mul_f32_e32 v80, v80, v136
	v_mul_f32_e32 v81, v81, v201
	v_mul_f32_e32 v81, v81, v137
	v_cvt_pk_bf16_f32 v78, v78, v79
	v_cvt_pk_bf16_f32 v79, v80, v81
	global_store_dwordx2 v[206:207], v[78:79], off offset:288
	s_waitcnt vmcnt(1)
	v_mul_f32_e32 v50, v50, v200
	v_mul_f32_e32 v50, v50, v138
	v_mul_f32_e32 v51, v51, v200
	v_mul_f32_e32 v51, v51, v139
	v_mul_f32_e32 v52, v52, v200
	v_mul_f32_e32 v52, v52, v140
	v_mul_f32_e32 v53, v53, v200
	v_mul_f32_e32 v53, v53, v141
	v_cvt_pk_bf16_f32 v50, v50, v51
	v_cvt_pk_bf16_f32 v51, v52, v53
	global_store_dwordx2 v[204:205], v[50:51], off offset:320
	v_mul_f32_e32 v54, v54, v201
	v_mul_f32_e32 v54, v54, v138
	v_mul_f32_e32 v55, v55, v201
	v_mul_f32_e32 v55, v55, v139
	v_mul_f32_e32 v56, v56, v201
	v_mul_f32_e32 v56, v56, v140
	v_mul_f32_e32 v57, v57, v201
	v_mul_f32_e32 v57, v57, v141
	v_cvt_pk_bf16_f32 v54, v54, v55
	v_cvt_pk_bf16_f32 v55, v56, v57
	global_store_dwordx2 v[206:207], v[54:55], off offset:320
	s_waitcnt vmcnt(0)
; __device__ __forceinline__ bf16_t f2bf(float x) { return (bf16_t)(cvt_pk_bf16(x, x) & 0xffffu); }
; __device__ __forceinline__ float bf2f(bf16_t b) { return __uint_as_float(((unsigned)b) << 16); }
; __device__ __forceinline__ int crow(int r, int hi) { return (r & 3) + 8 * (r >> 2) + 4 * hi; }
; __device__ __forceinline__ int crow(int r, int hi) { return (r & 3) + 8 * (r >> 2) + 4 * hi; }
; __device__ __forceinline__ void attn_body256(const bf16_t* __restrict__ Qb, const bf16_t* __restrict__ Kh, const bf16_t* __restrict__ Vh,
;                                              bf16_t* Ob, int seq, unsigned char* lds, float lam, int MODE, bf16_t* Ab, const float* wsub) {
;     ...
;   if (MODE == 0) {
; #pragma unroll
;     for (int r = 0; r < 16; ++r) { const int orow = crow(r, hi);
; #pragma unroll
;       for (int d0 = 0; d0 < 8; ++d0) Ow[(long)orow * LDO + d0 * 32 + r32] = f2bf(o[d0][r] * rli[r]); }
;     ...
;     for (int d0 = 0; d0 < 8; ++d0) wv[d0] = wsub[d0 * 32 + r32] * (1.f - LAMBDA_INIT);
; #pragma unroll
;     for (int r = 0; r < 16; ++r) { const int orow = crow(r, hi); float ss = 0.f;
; #pragma unroll
;       for (int d0 = 0; d0 < 8; ++d0) { const float v = bf2f(Ow[(long)orow * LDO + d0 * 32 + r32]) - lam * (o[d0][r] * rli[r]); o[d0][r] = v; ss += v * v; }
;       ss += __shfl_xor(ss, 1, 64); ss += __shfl_xor(ss, 2, 64); ss += __shfl_xor(ss, 4, 64); ss += __shfl_xor(ss, 8, 64); ss += __shfl_xor(ss, 16, 64);
;       const float rstd = rsqrtf(ss * (1.f / 256.f) + NORM_EPS);
; #pragma unroll
;       for (int d0 = 0; d0 < 8; ++d0) Aw[(long)orow * LDO + d0 * 32 + r32] = f2bf(o[d0][r] * rstd * wv[d0]); }
	v_mul_f32_e32 v58, v58, v200
	v_mul_f32_e32 v58, v58, v142
	v_mul_f32_e32 v59, v59, v200
	v_mul_f32_e32 v59, v59, v143
	v_mul_f32_e32 v60, v60, v200
	v_mul_f32_e32 v60, v60, v144
	v_mul_f32_e32 v61, v61, v200
	v_mul_f32_e32 v61, v61, v145
	v_cvt_pk_bf16_f32 v58, v58, v59
	v_cvt_pk_bf16_f32 v59, v60, v61
	global_store_dwordx2 v[204:205], v[58:59], off offset:352
	v_mul_f32_e32 v62, v62, v201
	v_mul_f32_e32 v62, v62, v142
	v_mul_f32_e32 v63, v63, v201
	v_mul_f32_e32 v63, v63, v143
	v_mul_f32_e32 v64, v64, v201
	v_mul_f32_e32 v64, v64, v144
	v_mul_f32_e32 v65, v65, v201
	v_mul_f32_e32 v65, v65, v145
	v_cvt_pk_bf16_f32 v62, v62, v63
	v_cvt_pk_bf16_f32 v63, v64, v65
	global_store_dwordx2 v[206:207], v[62:63], off offset:352
	global_load_dwordx4 v[130:133], v210, s[28:29] offset:768
	global_load_dwordx4 v[134:137], v210, s[28:29] offset:832
	global_load_dwordx4 v[138:141], v210, s[28:29] offset:896
	global_load_dwordx4 v[142:145], v210, s[28:29] offset:960
	s_waitcnt vmcnt(3)
	v_mul_f32_e32 v34, v34, v200
	v_mul_f32_e32 v34, v34, v130
	v_mul_f32_e32 v35, v35, v200
	v_mul_f32_e32 v35, v35, v131
	v_mul_f32_e32 v36, v36, v200
	v_mul_f32_e32 v36, v36, v132
	v_mul_f32_e32 v37, v37, v200
	v_mul_f32_e32 v37, v37, v133
	v_cvt_pk_bf16_f32 v34, v34, v35
	v_cvt_pk_bf16_f32 v35, v36, v37
	global_store_dwordx2 v[204:205], v[34:35], off offset:384
	v_mul_f32_e32 v38, v38, v201
	v_mul_f32_e32 v38, v38, v130
	v_mul_f32_e32 v39, v39, v201
	v_mul_f32_e32 v39, v39, v131
	v_mul_f32_e32 v40, v40, v201
	v_mul_f32_e32 v40, v40, v132
	v_mul_f32_e32 v41, v41, v201
	v_mul_f32_e32 v41, v41, v133
	v_cvt_pk_bf16_f32 v38, v38, v39
	v_cvt_pk_bf16_f32 v39, v40, v41
	global_store_dwordx2 v[206:207], v[38:39], off offset:384
	s_waitcnt vmcnt(2)
	v_mul_f32_e32 v42, v42, v200
	v_mul_f32_e32 v42, v42, v134
	v_mul_f32_e32 v43, v43, v200
	v_mul_f32_e32 v43, v43, v135
	v_mul_f32_e32 v44, v44, v200
	v_mul_f32_e32 v44, v44, v136
	v_mul_f32_e32 v45, v45, v200
	v_mul_f32_e32 v45, v45, v137
	v_cvt_pk_bf16_f32 v42, v42, v43
	v_cvt_pk_bf16_f32 v43, v44, v45
	global_store_dwordx2 v[204:205], v[42:43], off offset:416
	v_mul_f32_e32 v46, v46, v201
	v_mul_f32_e32 v46, v46, v134
	v_mul_f32_e32 v47, v47, v201
	v_mul_f32_e32 v47, v47, v135
	v_mul_f32_e32 v48, v48, v201
	v_mul_f32_e32 v48, v48, v136
	v_mul_f32_e32 v49, v49, v201
	v_mul_f32_e32 v49, v49, v137
	v_cvt_pk_bf16_f32 v46, v46, v47
	v_cvt_pk_bf16_f32 v47, v48, v49
	global_store_dwordx2 v[206:207], v[46:47], off offset:416
	s_waitcnt vmcnt(1)
	v_mul_f32_e32 v18, v18, v200
	v_mul_f32_e32 v18, v18, v138
	v_mul_f32_e32 v19, v19, v200
	v_mul_f32_e32 v19, v19, v139
	v_mul_f32_e32 v20, v20, v200
	v_mul_f32_e32 v20, v20, v140
	v_mul_f32_e32 v21, v21, v200
	v_mul_f32_e32 v21, v21, v141
	v_cvt_pk_bf16_f32 v18, v18, v19
	v_cvt_pk_bf16_f32 v19, v20, v21
	global_store_dwordx2 v[204:205], v[18:19], off offset:448
	v_mul_f32_e32 v22, v22, v201
	v_mul_f32_e32 v22, v22, v138
	v_mul_f32_e32 v23, v23, v201
	v_mul_f32_e32 v23, v23, v139
	v_mul_f32_e32 v24, v24, v201
	v_mul_f32_e32 v24, v24, v140
	v_mul_f32_e32 v25, v25, v201
	v_mul_f32_e32 v25, v25, v141
	v_cvt_pk_bf16_f32 v22, v22, v23
	v_cvt_pk_bf16_f32 v23, v24, v25
	global_store_dwordx2 v[206:207], v[22:23], off offset:448
	s_waitcnt vmcnt(0)
	v_mul_f32_e32 v26, v26, v200
	v_mul_f32_e32 v26, v26, v142
	v_mul_f32_e32 v27, v27, v200
	v_mul_f32_e32 v27, v27, v143
	v_mul_f32_e32 v28, v28, v200
	v_mul_f32_e32 v28, v28, v144
	v_mul_f32_e32 v29, v29, v200
	v_mul_f32_e32 v29, v29, v145
	v_cvt_pk_bf16_f32 v26, v26, v27
	v_cvt_pk_bf16_f32 v27, v28, v29
	global_store_dwordx2 v[204:205], v[26:27], off offset:480
	v_mul_f32_e32 v30, v30, v201
	v_mul_f32_e32 v30, v30, v142
	v_mul_f32_e32 v31, v31, v201
	v_mul_f32_e32 v31, v31, v143
	v_mul_f32_e32 v32, v32, v201
	v_mul_f32_e32 v32, v32, v144
	v_mul_f32_e32 v33, v33, v201
	v_mul_f32_e32 v33, v33, v145
	v_cvt_pk_bf16_f32 v30, v30, v31
	v_cvt_pk_bf16_f32 v31, v32, v33
	global_store_dwordx2 v[206:207], v[30:31], off offset:480
	v_readlane_b32 s28, v255, 4
	v_readlane_b32 s29, v255, 5
	s_mov_b32 s0, 0x3727c5ac
.Lat_e682:
	v_readlane_b32 s22, v255, 6
	s_andn2_b64 vcc, exec, s[10:11]
	v_readlane_b32 s0, v253, 42
	v_readlane_b32 s23, v255, 7
	s_cbranch_vccnz .LBB0_662
	s_mov_b32 s0, 1
	v_mul_f32_e32 v2, v2, v198
	v_mul_f32_e32 v3, v3, v198
	v_mul_f32_e32 v4, v4, v198
	v_mul_f32_e32 v5, v5, v198
	v_cvt_pk_bf16_f32 v2, v2, v3
	v_cvt_pk_bf16_f32 v3, v4, v5
	global_store_dwordx2 v[194:195], v[2:3], off
	v_mul_f32_e32 v10, v10, v198
	v_mul_f32_e32 v11, v11, v198
	v_mul_f32_e32 v12, v12, v198
	v_mul_f32_e32 v13, v13, v198
	v_cvt_pk_bf16_f32 v10, v10, v11
	v_cvt_pk_bf16_f32 v11, v12, v13
	global_store_dwordx2 v[194:195], v[10:11], off offset:32
	v_mul_f32_e32 v114, v114, v198
	v_mul_f32_e32 v115, v115, v198
	v_mul_f32_e32 v116, v116, v198
	v_mul_f32_e32 v117, v117, v198
	v_cvt_pk_bf16_f32 v114, v114, v115
	v_cvt_pk_bf16_f32 v115, v116, v117
	global_store_dwordx2 v[194:195], v[114:115], off offset:64
	v_mul_f32_e32 v122, v122, v198
	v_mul_f32_e32 v123, v123, v198
	v_mul_f32_e32 v124, v124, v198
	v_mul_f32_e32 v125, v125, v198
	v_cvt_pk_bf16_f32 v122, v122, v123
	v_cvt_pk_bf16_f32 v123, v124, v125
	global_store_dwordx2 v[194:195], v[122:123], off offset:96
	v_mul_f32_e32 v98, v98, v198
	v_mul_f32_e32 v99, v99, v198
	v_mul_f32_e32 v100, v100, v198
	v_mul_f32_e32 v101, v101, v198
	v_cvt_pk_bf16_f32 v98, v98, v99
	v_cvt_pk_bf16_f32 v99, v100, v101
	global_store_dwordx2 v[194:195], v[98:99], off offset:128
	v_mul_f32_e32 v106, v106, v198
	v_mul_f32_e32 v107, v107, v198
	v_mul_f32_e32 v108, v108, v198
	v_mul_f32_e32 v109, v109, v198
	v_cvt_pk_bf16_f32 v106, v106, v107
; __device__ __forceinline__ bf16_t f2bf(float x) { return (bf16_t)(cvt_pk_bf16(x, x) & 0xffffu); }
; __device__ __forceinline__ int crow(int r, int hi) { return (r & 3) + 8 * (r >> 2) + 4 * hi; }
; __device__ __forceinline__ int crow(int r, int hi) { return (r & 3) + 8 * (r >> 2) + 4 * hi; }
; __device__ __forceinline__ void attn_body256(const bf16_t* __restrict__ Qb, const bf16_t* __restrict__ Kh, const bf16_t* __restrict__ Vh,
;                                              bf16_t* Ob, int seq, unsigned char* lds, float lam, int MODE, bf16_t* Ab, const float* wsub) {
;     ...
;   if (MODE == 0) {
; #pragma unroll
;     for (int r = 0; r < 16; ++r) { const int orow = crow(r, hi);
; #pragma unroll
;       for (int d0 = 0; d0 < 8; ++d0) Ow[(long)orow * LDO + d0 * 32 + r32] = f2bf(o[d0][r] * rli[r]); }
	v_cvt_pk_bf16_f32 v107, v108, v109
	global_store_dwordx2 v[194:195], v[106:107], off offset:160
	v_mul_f32_e32 v82, v82, v198
	v_mul_f32_e32 v83, v83, v198
	v_mul_f32_e32 v84, v84, v198
	v_mul_f32_e32 v85, v85, v198
	v_cvt_pk_bf16_f32 v82, v82, v83
	v_cvt_pk_bf16_f32 v83, v84, v85
	global_store_dwordx2 v[194:195], v[82:83], off offset:192
	v_mul_f32_e32 v90, v90, v198
	v_mul_f32_e32 v91, v91, v198
	v_mul_f32_e32 v92, v92, v198
	v_mul_f32_e32 v93, v93, v198
	v_cvt_pk_bf16_f32 v90, v90, v91
	v_cvt_pk_bf16_f32 v91, v92, v93
	global_store_dwordx2 v[194:195], v[90:91], off offset:224
	v_mul_f32_e32 v66, v66, v198
	v_mul_f32_e32 v67, v67, v198
	v_mul_f32_e32 v68, v68, v198
	v_mul_f32_e32 v69, v69, v198
	v_cvt_pk_bf16_f32 v66, v66, v67
	v_cvt_pk_bf16_f32 v67, v68, v69
	global_store_dwordx2 v[194:195], v[66:67], off offset:256
	v_mul_f32_e32 v74, v74, v198
	v_mul_f32_e32 v75, v75, v198
	v_mul_f32_e32 v76, v76, v198
	v_mul_f32_e32 v77, v77, v198
	v_cvt_pk_bf16_f32 v74, v74, v75
	v_cvt_pk_bf16_f32 v75, v76, v77
	global_store_dwordx2 v[194:195], v[74:75], off offset:288
	v_mul_f32_e32 v50, v50, v198
	v_mul_f32_e32 v51, v51, v198
	v_mul_f32_e32 v52, v52, v198
	v_mul_f32_e32 v53, v53, v198
	v_cvt_pk_bf16_f32 v50, v50, v51
	v_cvt_pk_bf16_f32 v51, v52, v53
	global_store_dwordx2 v[194:195], v[50:51], off offset:320
	v_mul_f32_e32 v58, v58, v198
	v_mul_f32_e32 v59, v59, v198
	v_mul_f32_e32 v60, v60, v198
	v_mul_f32_e32 v61, v61, v198
	v_cvt_pk_bf16_f32 v58, v58, v59
	v_cvt_pk_bf16_f32 v59, v60, v61
	global_store_dwordx2 v[194:195], v[58:59], off offset:352
	v_mul_f32_e32 v34, v34, v198
	v_mul_f32_e32 v35, v35, v198
	v_mul_f32_e32 v36, v36, v198
	v_mul_f32_e32 v37, v37, v198
	v_cvt_pk_bf16_f32 v34, v34, v35
	v_cvt_pk_bf16_f32 v35, v36, v37
	global_store_dwordx2 v[194:195], v[34:35], off offset:384
	v_mul_f32_e32 v42, v42, v198
	v_mul_f32_e32 v43, v43, v198
	v_mul_f32_e32 v44, v44, v198
	v_mul_f32_e32 v45, v45, v198
	v_cvt_pk_bf16_f32 v42, v42, v43
	v_cvt_pk_bf16_f32 v43, v44, v45
	global_store_dwordx2 v[194:195], v[42:43], off offset:416
	v_mul_f32_e32 v18, v18, v198
	v_mul_f32_e32 v19, v19, v198
	v_mul_f32_e32 v20, v20, v198
	v_mul_f32_e32 v21, v21, v198
	v_cvt_pk_bf16_f32 v18, v18, v19
	v_cvt_pk_bf16_f32 v19, v20, v21
	global_store_dwordx2 v[194:195], v[18:19], off offset:448
	v_mul_f32_e32 v26, v26, v198
	v_mul_f32_e32 v27, v27, v198
	v_mul_f32_e32 v28, v28, v198
	v_mul_f32_e32 v29, v29, v198
	v_cvt_pk_bf16_f32 v26, v26, v27
	v_cvt_pk_bf16_f32 v27, v28, v29
	global_store_dwordx2 v[194:195], v[26:27], off offset:480
	v_mul_f32_e32 v6, v6, v199
	v_mul_f32_e32 v7, v7, v199
	v_mul_f32_e32 v8, v8, v199
	v_mul_f32_e32 v9, v9, v199
	v_cvt_pk_bf16_f32 v6, v6, v7
	v_cvt_pk_bf16_f32 v7, v8, v9
	global_store_dwordx2 v[196:197], v[6:7], off
	v_mul_f32_e32 v14, v14, v199
	v_mul_f32_e32 v15, v15, v199
	v_mul_f32_e32 v16, v16, v199
	v_mul_f32_e32 v17, v17, v199
	v_cvt_pk_bf16_f32 v14, v14, v15
	v_cvt_pk_bf16_f32 v15, v16, v17
	global_store_dwordx2 v[196:197], v[14:15], off offset:32
	v_mul_f32_e32 v118, v118, v199
	v_mul_f32_e32 v119, v119, v199
	v_mul_f32_e32 v120, v120, v199
	v_mul_f32_e32 v121, v121, v199
	v_cvt_pk_bf16_f32 v118, v118, v119
	v_cvt_pk_bf16_f32 v119, v120, v121
	global_store_dwordx2 v[196:197], v[118:119], off offset:64
	v_mul_f32_e32 v126, v126, v199
	v_mul_f32_e32 v127, v127, v199
	v_mul_f32_e32 v128, v128, v199
	v_mul_f32_e32 v129, v129, v199
	v_cvt_pk_bf16_f32 v126, v126, v127
	v_cvt_pk_bf16_f32 v127, v128, v129
	global_store_dwordx2 v[196:197], v[126:127], off offset:96
	v_mul_f32_e32 v102, v102, v199
	v_mul_f32_e32 v103, v103, v199
	v_mul_f32_e32 v104, v104, v199
	v_mul_f32_e32 v105, v105, v199
	v_cvt_pk_bf16_f32 v102, v102, v103
	v_cvt_pk_bf16_f32 v103, v104, v105
	global_store_dwordx2 v[196:197], v[102:103], off offset:128
	v_mul_f32_e32 v110, v110, v199
	v_mul_f32_e32 v111, v111, v199
	v_mul_f32_e32 v112, v112, v199
	v_mul_f32_e32 v113, v113, v199
	v_cvt_pk_bf16_f32 v110, v110, v111
	v_cvt_pk_bf16_f32 v111, v112, v113
	global_store_dwordx2 v[196:197], v[110:111], off offset:160
	v_mul_f32_e32 v86, v86, v199
	v_mul_f32_e32 v87, v87, v199
	v_mul_f32_e32 v88, v88, v199
	v_mul_f32_e32 v89, v89, v199
	v_cvt_pk_bf16_f32 v86, v86, v87
	v_cvt_pk_bf16_f32 v87, v88, v89
	global_store_dwordx2 v[196:197], v[86:87], off offset:192
	v_mul_f32_e32 v94, v94, v199
	v_mul_f32_e32 v95, v95, v199
	v_mul_f32_e32 v96, v96, v199
	v_mul_f32_e32 v97, v97, v199
	v_cvt_pk_bf16_f32 v94, v94, v95
	v_cvt_pk_bf16_f32 v95, v96, v97
	global_store_dwordx2 v[196:197], v[94:95], off offset:224
	v_mul_f32_e32 v70, v70, v199
	v_mul_f32_e32 v71, v71, v199
	v_mul_f32_e32 v72, v72, v199
	v_mul_f32_e32 v73, v73, v199
	v_cvt_pk_bf16_f32 v70, v70, v71
	v_cvt_pk_bf16_f32 v71, v72, v73
	global_store_dwordx2 v[196:197], v[70:71], off offset:256
	v_mul_f32_e32 v78, v78, v199
	v_mul_f32_e32 v79, v79, v199
	v_mul_f32_e32 v80, v80, v199
	v_mul_f32_e32 v81, v81, v199
	v_cvt_pk_bf16_f32 v78, v78, v79
	v_cvt_pk_bf16_f32 v79, v80, v81
	global_store_dwordx2 v[196:197], v[78:79], off offset:288
	v_mul_f32_e32 v54, v54, v199
	v_mul_f32_e32 v55, v55, v199
	v_mul_f32_e32 v56, v56, v199
	v_mul_f32_e32 v57, v57, v199
	v_cvt_pk_bf16_f32 v54, v54, v55
	v_cvt_pk_bf16_f32 v55, v56, v57
	global_store_dwordx2 v[196:197], v[54:55], off offset:320
	v_mul_f32_e32 v62, v62, v199
	v_mul_f32_e32 v63, v63, v199
	v_mul_f32_e32 v64, v64, v199
	v_mul_f32_e32 v65, v65, v199
	v_cvt_pk_bf16_f32 v62, v62, v63
	v_cvt_pk_bf16_f32 v63, v64, v65
	global_store_dwordx2 v[196:197], v[62:63], off offset:352
	v_mul_f32_e32 v38, v38, v199
	v_mul_f32_e32 v39, v39, v199
	v_mul_f32_e32 v40, v40, v199
	v_mul_f32_e32 v41, v41, v199
	v_cvt_pk_bf16_f32 v38, v38, v39
	v_cvt_pk_bf16_f32 v39, v40, v41
	global_store_dwordx2 v[196:197], v[38:39], off offset:384
	v_mul_f32_e32 v46, v46, v199
	v_mul_f32_e32 v47, v47, v199
	v_mul_f32_e32 v48, v48, v199
	v_mul_f32_e32 v49, v49, v199
	v_cvt_pk_bf16_f32 v46, v46, v47
	v_cvt_pk_bf16_f32 v47, v48, v49
	global_store_dwordx2 v[196:197], v[46:47], off offset:416
	v_mul_f32_e32 v22, v22, v199
	v_mul_f32_e32 v23, v23, v199
	v_mul_f32_e32 v24, v24, v199
	v_mul_f32_e32 v25, v25, v199
	v_cvt_pk_bf16_f32 v22, v22, v23
	v_cvt_pk_bf16_f32 v23, v24, v25
	global_store_dwordx2 v[196:197], v[22:23], off offset:448
	v_mul_f32_e32 v30, v30, v199
	v_mul_f32_e32 v31, v31, v199
	v_mul_f32_e32 v32, v32, v199
	v_mul_f32_e32 v33, v33, v199
	v_cvt_pk_bf16_f32 v30, v30, v31
	v_cvt_pk_bf16_f32 v31, v32, v33
	global_store_dwordx2 v[196:197], v[30:31], off offset:480
	s_branch .LBB0_662
; __device__ __forceinline__ unsigned xb_add(unsigned* p, unsigned v) { return __hip_atomic_fetch_add(p, v, __ATOMIC_RELAXED, __HIP_MEMORY_SCOPE_AGENT); }
; __device__ __forceinline__ void xcd_barrier(const XcdBarrier& b) {
;     asm volatile("s_waitcnt vmcnt(0)" ::: "memory");
;     __syncthreads();
;     if (threadIdx.x == 0) {
;         unsigned* bar = b.bar;
;         __builtin_amdgcn_s_waitcnt(0);
;         unsigned nloc = b.st[0], nx = b.st[1];
;         if (nloc == 0u) { xcd_barrier_complete(bar, b.x, nloc, nx); b.st[0] = nloc; b.st[1] = nx; }
;         const unsigned old = xb_add(&bar[XB_XSUB(b.x)], 1u);
.LBB0_684:
	v_mov_b64_e32 v[210:211], 0x3ff
	v_mov_b64_e32 v[212:213], 0x400
	v_mov_b32_e32 v244, 0x3727c5ac
	v_mov_b32_e32 v245, 0x41b17218
	s_getreg_b32 s2, hwreg(HW_REG_XCC_ID, 0, 4)
	s_waitcnt vmcnt(0)
	s_barrier
	s_mov_b64 s[0:1], exec
	v_readlane_b32 s6, v252, 0
	v_readlane_b32 s7, v252, 1
	s_and_b64 s[6:7], s[0:1], s[6:7]
	s_mov_b64 exec, s[6:7]
	s_cbranch_execz .LBB0_736
	v_readlane_b32 s6, v254, 43
	s_waitcnt vmcnt(0) expcnt(0) lgkmcnt(0)
	s_and_b32 s2, s2, 15
	v_mov_b32_e32 v0, s6
	ds_read_b32 v3, v0
	v_readlane_b32 s6, v254, 44
	s_waitcnt lgkmcnt(0)
	v_cmp_ne_u32_e32 vcc, 0, v3
	v_mov_b32_e32 v0, s6
	ds_read_b32 v2, v0
	s_cbranch_vccnz .LBB0_700
	s_mov_b32 s12, 1
	s_branch .LBB0_688
